# NSA window-branch and compressed pass-A tile loops hand-scheduled (range masks only on edge tiles via per-lane 64-bit visibility masks), pass-B quad shuffles via DPP
# speedup vs baseline: 1.2357x; 1.0246x over previous
.LBB0_834:
	v_writelane_b32 v248, s47, 14
	s_or_b64 exec, exec, s[2:3]
	v_readfirstlane_b32 s2, v104
	s_lshr_b32 s33, s2, 6
	s_lshl_b32 s2, s58, 5
	s_lshl_b32 s3, s33, 3
	v_writelane_b32 v248, s2, 16
	v_writelane_b32 v248, s3, 24
	s_add_i32 s46, s3, s2
	v_readlane_b32 s42, v248, 6
	v_or_b32_e32 v184, s46, v164
	s_lshl_b32 s2, s42, 12
	v_readlane_b32 s3, v248, 12
	v_or_b32_e32 v185, 4, v184
	v_mov_b32_e32 v1, v117
	v_lshl_or_b32 v0, s3, 23, v123
	v_add_u32_e32 v152, s2, v184
	v_mov_b32_e32 v153, v117
	v_add_u32_e32 v150, s2, v185
	v_mov_b32_e32 v151, v117
	v_lshl_add_u64 v[8:9], v[118:119], 0, v[0:1]
	v_lshlrev_b64 v[148:149], 7, v[152:153]
	v_lshlrev_b64 v[146:147], 7, v[150:151]
	v_lshl_add_u64 v[4:5], v[8:9], 0, v[148:149]
	v_lshl_add_u64 v[12:13], v[8:9], 0, v[146:147]
	s_barrier
	global_load_dwordx4 v[0:3], v[4:5], off
	s_nop 0
	global_load_dwordx4 v[4:7], v[4:5], off offset:64
	s_nop 0
	global_load_dwordx4 v[8:11], v[12:13], off
	s_nop 0
	global_load_dwordx4 v[12:15], v[12:13], off offset:64
	s_lshl_b32 s2, s42, 1
	s_mov_b32 s41, s45
	s_or_b32 s40, s2, s3
	v_readlane_b32 s43, v248, 7
	v_writelane_b32 v248, s40, 25
	v_lshl_or_b32 v145, s3, 2, v115
	s_lshl_b64 s[2:3], s[40:41], 15
	v_writelane_b32 v248, s41, 26
	s_lshr_b32 s38, s58, 5
	v_lshl_add_u64 v[154:155], v[132:133], 0, s[2:3]
	v_lshl_add_u64 v[156:157], v[134:135], 0, s[2:3]
	v_readlane_b32 s2, v248, 14
	v_mul_u32_u24_e32 v16, 3, v145
	v_readlane_b32 s48, v250, 0
	s_movk_i32 s47, 0x1000
	s_cmpk_gt_u32 s2, 0xbf
	v_mov_b32_e32 v17, v117
	v_lshlrev_b32_e32 v16, 2, v16
	v_readlane_b32 s49, v250, 1
	v_add_co_u32_e32 v18, vcc, s47, v154
	s_cselect_b32 s39, 0, 64
	v_lshl_add_u64 v[16:17], s[48:49], 0, v[16:17]
	v_addc_co_u32_e32 v19, vcc, 0, v155, vcc
	s_movk_i32 s48, 0x4000
	s_lshl_b32 s44, s39, 1
	v_add_co_u32_e32 v20, vcc, s48, v156
	v_lshl_add_u64 v[32:33], v[156:157], 0, s[44:45]
	s_lshl_b32 s44, s39, 7
	v_addc_co_u32_e32 v21, vcc, 0, v157, vcc
	v_lshl_add_u64 v[34:35], v[154:155], 0, s[44:45]
	v_add_co_u32_e32 v24, vcc, s47, v34
	s_movk_i32 s40, 0x60
	s_nop 0
	v_addc_co_u32_e32 v25, vcc, 0, v35, vcc
	v_add_co_u32_e32 v28, vcc, 0x4000, v32
	global_load_dwordx4 v[36:39], v[154:155], off
	global_load_dwordx4 v[44:47], v[156:157], off
	global_load_dwordx4 v[48:51], v[18:19], off
	global_load_dwordx4 v[52:55], v[20:21], off
	v_mad_u64_u32 v[18:19], s[2:3], v152, s40, v[16:17]
	v_mad_u64_u32 v[16:17], s[2:3], v150, s40, v[16:17]
	v_addc_co_u32_e32 v29, vcc, 0, v33, vcc
	global_load_dwordx3 v[80:82], v[18:19], off
	global_load_dwordx3 v[76:78], v[16:17], off
	s_mov_b32 s43, s45
	s_mov_b64 s[2:3], 0x1000
	s_mov_b64 s[40:41], 0x4000
	v_mov_b32_e32 v60, 0
	v_writelane_b32 v248, s42, 6
	v_lshl_add_u64 v[40:41], v[154:155], 0, s[2:3]
	s_mov_b32 s39, 0
	v_lshl_add_u64 v[42:43], v[156:157], 0, s[40:41]
	v_mov_b32_e32 v61, v60
	v_readlane_b32 s50, v250, 2
	v_readlane_b32 s51, v250, 3
	s_waitcnt vmcnt(8)
	s_waitcnt vmcnt(6)
	global_load_dwordx4 v[16:19], v[32:33], off
	global_load_dwordx4 v[20:23], v[34:35], off
	s_nop 0
	global_load_dwordx4 v[24:27], v[24:25], off
	s_nop 0
	global_load_dwordx4 v[28:31], v[28:29], off
	s_waitcnt vmcnt(9)
	ds_write_b128 v127, v[36:39]
	s_waitcnt vmcnt(8)
	ds_write_b128 v127, v[44:47] offset:18432
	s_waitcnt vmcnt(7)
	ds_write_b128 v127, v[48:51] offset:4608
	s_waitcnt vmcnt(6)
	ds_write_b128 v127, v[52:55] offset:23040
	v_subrev_u32_e32 v44, 27, v184
	v_subrev_u32_e32 v45, 31, v184
	v_lshl_add_u64 v[36:37], v[34:35], 0, s[2:3]
	v_lshl_add_u64 v[38:39], v[32:33], 0, s[40:41]
	v_ashrrev_i32_e32 v113, 4, v45
	v_ashrrev_i32_e32 v158, 4, v44
	s_add_i32 s40, s38, 1
	s_mov_b32 s41, 0
	v_readlane_b32 s52, v250, 4
	v_readlane_b32 s53, v250, 5
	v_readlane_b32 s54, v250, 6
	v_readlane_b32 s55, v250, 7
	v_writelane_b32 v248, s43, 7
	s_waitcnt lgkmcnt(0)
	s_barrier
	ds_read_b128 v[186:189], v129 offset:0
	ds_read_b128 v[190:193], v129 offset:64
	ds_read_b128 v[194:197], v129 offset:2304
	ds_read_b128 v[198:201], v129 offset:2368
	v_mov_b32_e32 v54, v61
	v_mov_b32_e32 v55, 0
	v_mov_b32_e32 v56, v60
	v_mov_b32_e32 v57, 0
.LBB0_835:
	s_cmp_eq_u32 s41, s38
	s_cbranch_scc1 .Lcmpa_masked
	s_and_b32 s42, s41, 1
	s_xor_b32 s2, s42, 1
	s_mulk_i32 s2, 0x2400
	s_mulk_i32 s42, 0x2400
	v_add_u32_e32 v44, s42, v129
	v_add_u32_e32 v45, s2, v127
	ds_read_b128 v[202:205], v44 offset:4608
	ds_read_b128 v[206:209], v44 offset:4672
	ds_read_b128 v[210:213], v44 offset:6912
	ds_read_b128 v[218:221], v44 offset:6976
	v_add_u32_e32 v44, s2, v129
	s_waitcnt lgkmcnt(5)
	v_mfma_f32_16x16x32_bf16 v[64:67], v[186:189], v[0:3], 0
	v_mfma_f32_16x16x32_bf16 v[68:71], v[186:189], v[8:11], 0
	v_mfma_f32_16x16x32_bf16 v[222:225], v[194:197], v[0:3], 0
	v_mfma_f32_16x16x32_bf16 v[226:229], v[194:197], v[8:11], 0
	s_waitcnt vmcnt(1)
	ds_write_b128 v45, v[20:23]
	s_waitcnt lgkmcnt(5)
	v_mfma_f32_16x16x32_bf16 v[64:67], v[190:193], v[4:7], v[64:67]
	v_mfma_f32_16x16x32_bf16 v[68:71], v[190:193], v[12:15], v[68:71]
	v_mfma_f32_16x16x32_bf16 v[222:225], v[198:201], v[4:7], v[222:225]
	v_mfma_f32_16x16x32_bf16 v[226:229], v[198:201], v[12:15], v[226:229]
	s_waitcnt vmcnt(0)
	ds_write_b128 v45, v[24:27] offset:4608
	s_add_i32 s2, s41, 2
	s_min_i32 s43, s2, s38
	s_lshl_b32 s44, s43, 13
	v_lshl_add_u64 v[20:21], v[154:155], 0, s[44:45]
	v_add_co_u32_e32 v24, vcc, s47, v20
	s_nop 0
	v_addc_co_u32_e32 v25, vcc, 0, v21, vcc
	global_load_dwordx4 v[20:23], v[20:21], off
	global_load_dwordx4 v[24:27], v[24:25], off
	s_waitcnt lgkmcnt(3)
	v_mfma_f32_16x16x32_bf16 v[230:233], v[202:205], v[0:3], 0
	v_mfma_f32_16x16x32_bf16 v[234:237], v[202:205], v[8:11], 0
	v_mfma_f32_16x16x32_bf16 v[238:241], v[210:213], v[0:3], 0
	v_mfma_f32_16x16x32_bf16 v[242:245], v[210:213], v[8:11], 0
	s_waitcnt lgkmcnt(2)
	v_mfma_f32_16x16x32_bf16 v[230:233], v[206:209], v[4:7], v[230:233]
	v_mfma_f32_16x16x32_bf16 v[234:237], v[206:209], v[12:15], v[234:237]
	v_mfma_f32_16x16x32_bf16 v[238:241], v[218:221], v[4:7], v[238:241]
	v_mfma_f32_16x16x32_bf16 v[242:245], v[218:221], v[12:15], v[242:245]
	s_setprio 0
	s_add_i32 s41, s41, 1
	s_add_i32 s39, s39, 64
	v_exp_f32_e32 v64, v64
	v_exp_f32_e32 v68, v68
	v_exp_f32_e32 v65, v65
	v_exp_f32_e32 v69, v69
	v_exp_f32_e32 v66, v66
	v_exp_f32_e32 v70, v70
	v_exp_f32_e32 v67, v67
	v_exp_f32_e32 v71, v71
	v_pk_add_f32 v[54:55], v[54:55], v[64:65]
	v_pk_add_f32 v[56:57], v[56:57], v[68:69]
	v_pk_add_f32 v[54:55], v[54:55], v[66:67]
	v_pk_add_f32 v[56:57], v[56:57], v[70:71]
	v_exp_f32_e32 v222, v222
	v_exp_f32_e32 v226, v226
	v_exp_f32_e32 v223, v223
	v_exp_f32_e32 v227, v227
	v_exp_f32_e32 v224, v224
	v_exp_f32_e32 v228, v228
	v_exp_f32_e32 v225, v225
	v_exp_f32_e32 v229, v229
	v_pk_add_f32 v[54:55], v[54:55], v[222:223]
	v_pk_add_f32 v[56:57], v[56:57], v[226:227]
	v_pk_add_f32 v[54:55], v[54:55], v[224:225]
	v_pk_add_f32 v[56:57], v[56:57], v[228:229]
	s_waitcnt lgkmcnt(0)
	s_barrier
	ds_read_b128 v[186:189], v44 offset:0
	ds_read_b128 v[190:193], v44 offset:64
	ds_read_b128 v[194:197], v44 offset:2304
	ds_read_b128 v[198:201], v44 offset:2368
	v_exp_f32_e32 v230, v230
	v_exp_f32_e32 v234, v234
	v_exp_f32_e32 v231, v231
	v_exp_f32_e32 v235, v235
	v_exp_f32_e32 v232, v232
	v_exp_f32_e32 v236, v236
	v_exp_f32_e32 v233, v233
	v_exp_f32_e32 v237, v237
	v_pk_add_f32 v[54:55], v[54:55], v[230:231]
	v_pk_add_f32 v[56:57], v[56:57], v[234:235]
	v_pk_add_f32 v[54:55], v[54:55], v[232:233]
	v_pk_add_f32 v[56:57], v[56:57], v[236:237]
	v_exp_f32_e32 v238, v238
	v_exp_f32_e32 v242, v242
	v_exp_f32_e32 v239, v239
	v_exp_f32_e32 v243, v243
	v_exp_f32_e32 v240, v240
	v_exp_f32_e32 v244, v244
	v_exp_f32_e32 v241, v241
	v_exp_f32_e32 v245, v245
	v_pk_add_f32 v[54:55], v[54:55], v[238:239]
	v_pk_add_f32 v[56:57], v[56:57], v[242:243]
	v_pk_add_f32 v[54:55], v[54:55], v[240:241]
	v_pk_add_f32 v[56:57], v[56:57], v[244:245]
	s_setprio 2
	s_cmp_lg_u32 s40, s41
	s_cbranch_scc1 .LBB0_835
	s_branch .Lcmpa_done
.Lcmpa_masked:
	s_and_b32 s42, s41, 1
	s_xor_b32 s2, s42, 1
	s_mulk_i32 s2, 0x2400
	s_mulk_i32 s42, 0x2400
	v_add_u32_e32 v44, s42, v129
	v_add_u32_e32 v45, s2, v127
	ds_read_b128 v[202:205], v44 offset:4608
	ds_read_b128 v[206:209], v44 offset:4672
	ds_read_b128 v[210:213], v44 offset:6912
	ds_read_b128 v[218:221], v44 offset:6976
	v_add_u32_e32 v44, s2, v129
	v_subrev_u32_e32 v50, s39, v113
	v_ashrrev_i32_e32 v51, 31, v50
	v_med3_i32 v50, v50, 0, 63
	v_sub_u32_e32 v50, 63, v50
	v_not_b32_e32 v46, v51
	v_mov_b32_e32 v47, v46
	v_lshrrev_b64 v[46:47], v50, v[46:47]
	v_lshrrev_b32_e32 v46, v112, v46
	v_lshrrev_b32_e32 v47, v112, v47
	v_subrev_u32_e32 v50, s39, v158
	v_ashrrev_i32_e32 v51, 31, v50
	v_med3_i32 v50, v50, 0, 63
	v_sub_u32_e32 v50, 63, v50
	v_not_b32_e32 v48, v51
	v_mov_b32_e32 v49, v48
	v_lshrrev_b64 v[48:49], v50, v[48:49]
	v_lshrrev_b32_e32 v48, v112, v48
	v_lshrrev_b32_e32 v49, v112, v49
	s_waitcnt lgkmcnt(5)
	v_mfma_f32_16x16x32_bf16 v[64:67], v[186:189], v[0:3], 0
	v_mfma_f32_16x16x32_bf16 v[68:71], v[186:189], v[8:11], 0
	v_mfma_f32_16x16x32_bf16 v[222:225], v[194:197], v[0:3], 0
	v_mfma_f32_16x16x32_bf16 v[226:229], v[194:197], v[8:11], 0
	s_waitcnt vmcnt(1)
	ds_write_b128 v45, v[20:23]
	s_waitcnt lgkmcnt(5)
	v_mfma_f32_16x16x32_bf16 v[64:67], v[190:193], v[4:7], v[64:67]
	v_mfma_f32_16x16x32_bf16 v[68:71], v[190:193], v[12:15], v[68:71]
	v_mfma_f32_16x16x32_bf16 v[222:225], v[198:201], v[4:7], v[222:225]
	v_mfma_f32_16x16x32_bf16 v[226:229], v[198:201], v[12:15], v[226:229]
	s_waitcnt vmcnt(0)
	ds_write_b128 v45, v[24:27] offset:4608
	s_add_i32 s2, s41, 2
	s_min_i32 s43, s2, s38
	s_lshl_b32 s44, s43, 13
	v_lshl_add_u64 v[20:21], v[154:155], 0, s[44:45]
	v_add_co_u32_e32 v24, vcc, s47, v20
	s_nop 0
	v_addc_co_u32_e32 v25, vcc, 0, v21, vcc
	global_load_dwordx4 v[20:23], v[20:21], off
	global_load_dwordx4 v[24:27], v[24:25], off
	s_waitcnt lgkmcnt(3)
	v_mfma_f32_16x16x32_bf16 v[230:233], v[202:205], v[0:3], 0
	v_mfma_f32_16x16x32_bf16 v[234:237], v[202:205], v[8:11], 0
	v_mfma_f32_16x16x32_bf16 v[238:241], v[210:213], v[0:3], 0
	v_mfma_f32_16x16x32_bf16 v[242:245], v[210:213], v[8:11], 0
	s_waitcnt lgkmcnt(2)
	v_mfma_f32_16x16x32_bf16 v[230:233], v[206:209], v[4:7], v[230:233]
	v_mfma_f32_16x16x32_bf16 v[234:237], v[206:209], v[12:15], v[234:237]
	v_mfma_f32_16x16x32_bf16 v[238:241], v[218:221], v[4:7], v[238:241]
	v_mfma_f32_16x16x32_bf16 v[242:245], v[218:221], v[12:15], v[242:245]
	s_setprio 0
	s_add_i32 s41, s41, 1
	s_add_i32 s39, s39, 64
	v_exp_f32_e32 v64, v64
	v_exp_f32_e32 v68, v68
	v_exp_f32_e32 v65, v65
	v_exp_f32_e32 v69, v69
	v_exp_f32_e32 v66, v66
	v_exp_f32_e32 v70, v70
	v_exp_f32_e32 v67, v67
	v_exp_f32_e32 v71, v71
	v_bfe_i32 v50, v46, 0, 1
	v_bfe_i32 v52, v48, 0, 1
	v_bfe_i32 v51, v46, 1, 1
	v_bfe_i32 v53, v48, 1, 1
	v_and_b32_e32 v64, v50, v64
	v_and_b32_e32 v68, v52, v68
	v_and_b32_e32 v65, v51, v65
	v_and_b32_e32 v69, v53, v69
	v_bfe_i32 v50, v46, 2, 1
	v_bfe_i32 v52, v48, 2, 1
	v_bfe_i32 v51, v46, 3, 1
	v_bfe_i32 v53, v48, 3, 1
	v_and_b32_e32 v66, v50, v66
	v_and_b32_e32 v70, v52, v70
	v_and_b32_e32 v67, v51, v67
	v_and_b32_e32 v71, v53, v71
	v_pk_add_f32 v[54:55], v[54:55], v[64:65]
	v_pk_add_f32 v[56:57], v[56:57], v[68:69]
	v_pk_add_f32 v[54:55], v[54:55], v[66:67]
	v_pk_add_f32 v[56:57], v[56:57], v[70:71]
	v_exp_f32_e32 v222, v222
	v_exp_f32_e32 v226, v226
	v_exp_f32_e32 v223, v223
	v_exp_f32_e32 v227, v227
	v_exp_f32_e32 v224, v224
	v_exp_f32_e32 v228, v228
	v_exp_f32_e32 v225, v225
	v_exp_f32_e32 v229, v229
	v_bfe_i32 v50, v46, 16, 1
	v_bfe_i32 v52, v48, 16, 1
	v_bfe_i32 v51, v46, 17, 1
	v_bfe_i32 v53, v48, 17, 1
	v_and_b32_e32 v222, v50, v222
	v_and_b32_e32 v226, v52, v226
	v_and_b32_e32 v223, v51, v223
	v_and_b32_e32 v227, v53, v227
	v_bfe_i32 v50, v46, 18, 1
	v_bfe_i32 v52, v48, 18, 1
	v_bfe_i32 v51, v46, 19, 1
	v_bfe_i32 v53, v48, 19, 1
	v_and_b32_e32 v224, v50, v224
	v_and_b32_e32 v228, v52, v228
	v_and_b32_e32 v225, v51, v225
	v_and_b32_e32 v229, v53, v229
	v_pk_add_f32 v[54:55], v[54:55], v[222:223]
	v_pk_add_f32 v[56:57], v[56:57], v[226:227]
	v_pk_add_f32 v[54:55], v[54:55], v[224:225]
	v_pk_add_f32 v[56:57], v[56:57], v[228:229]
	s_waitcnt lgkmcnt(0)
	s_barrier
	ds_read_b128 v[186:189], v44 offset:0
	ds_read_b128 v[190:193], v44 offset:64
	ds_read_b128 v[194:197], v44 offset:2304
	ds_read_b128 v[198:201], v44 offset:2368
	v_exp_f32_e32 v230, v230
	v_exp_f32_e32 v234, v234
	v_exp_f32_e32 v231, v231
	v_exp_f32_e32 v235, v235
	v_exp_f32_e32 v232, v232
	v_exp_f32_e32 v236, v236
	v_exp_f32_e32 v233, v233
	v_exp_f32_e32 v237, v237
	v_bfe_i32 v50, v47, 0, 1
	v_bfe_i32 v52, v49, 0, 1
	v_bfe_i32 v51, v47, 1, 1
	v_bfe_i32 v53, v49, 1, 1
	v_and_b32_e32 v230, v50, v230
	v_and_b32_e32 v234, v52, v234
	v_and_b32_e32 v231, v51, v231
	v_and_b32_e32 v235, v53, v235
	v_bfe_i32 v50, v47, 2, 1
	v_bfe_i32 v52, v49, 2, 1
	v_bfe_i32 v51, v47, 3, 1
	v_bfe_i32 v53, v49, 3, 1
	v_and_b32_e32 v232, v50, v232
	v_and_b32_e32 v236, v52, v236
	v_and_b32_e32 v233, v51, v233
	v_and_b32_e32 v237, v53, v237
	v_pk_add_f32 v[54:55], v[54:55], v[230:231]
	v_pk_add_f32 v[56:57], v[56:57], v[234:235]
	v_pk_add_f32 v[54:55], v[54:55], v[232:233]
	v_pk_add_f32 v[56:57], v[56:57], v[236:237]
	v_exp_f32_e32 v238, v238
	v_exp_f32_e32 v242, v242
	v_exp_f32_e32 v239, v239
	v_exp_f32_e32 v243, v243
	v_exp_f32_e32 v240, v240
	v_exp_f32_e32 v244, v244
	v_exp_f32_e32 v241, v241
	v_exp_f32_e32 v245, v245
	v_bfe_i32 v50, v47, 16, 1
	v_bfe_i32 v52, v49, 16, 1
	v_bfe_i32 v51, v47, 17, 1
	v_bfe_i32 v53, v49, 17, 1
	v_and_b32_e32 v238, v50, v238
	v_and_b32_e32 v242, v52, v242
	v_and_b32_e32 v239, v51, v239
	v_and_b32_e32 v243, v53, v243
	v_bfe_i32 v50, v47, 18, 1
	v_bfe_i32 v52, v49, 18, 1
	v_bfe_i32 v51, v47, 19, 1
	v_bfe_i32 v53, v49, 19, 1
	v_and_b32_e32 v240, v50, v240
	v_and_b32_e32 v244, v52, v244
	v_and_b32_e32 v241, v51, v241
	v_and_b32_e32 v245, v53, v245
	v_pk_add_f32 v[54:55], v[54:55], v[238:239]
	v_pk_add_f32 v[56:57], v[56:57], v[242:243]
	v_pk_add_f32 v[54:55], v[54:55], v[240:241]
	v_pk_add_f32 v[56:57], v[56:57], v[244:245]
	s_setprio 2
	s_cmp_lg_u32 s40, s41
	s_cbranch_scc1 .LBB0_835
.Lcmpa_done:
	s_waitcnt lgkmcnt(0)
	s_setprio 0
	v_add_f32_e32 v61, v54, v55
	v_add_f32_e32 v60, v56, v57
	global_load_dwordx4 v[62:65], v[154:155], off
	global_load_dwordx4 v[66:69], v[156:157], off
	global_load_dwordx4 v[70:73], v[40:41], off
	global_load_dwordx4 v[188:191], v[42:43], off
	global_load_dwordx4 v[16:19], v[32:33], off
	global_load_dwordx4 v[20:23], v[34:35], off
	global_load_dwordx4 v[24:27], v[36:37], off
	global_load_dwordx4 v[28:31], v[38:39], off
	v_and_b32_e32 v33, 64, v121
	v_xor_b32_e32 v59, 16, v121
	v_add_u32_e32 v187, 64, v33
	v_cmp_lt_i32_e32 vcc, v59, v187
	v_xor_b32_e32 v162, 32, v121
	v_xor_b32_e32 v163, 1, v121
	v_cndmask_b32_e32 v59, v121, v59, vcc
	v_lshlrev_b32_e32 v182, 2, v59
	ds_bpermute_b32 v75, v182, v61
	ds_bpermute_b32 v74, v182, v60
	v_cmp_lt_i32_e32 vcc, v162, v187
	v_xor_b32_e32 v186, 2, v121
	s_mul_i32 s42, s33, 0x1020
	v_cndmask_b32_e32 v162, v121, v162, vcc
	v_lshlrev_b32_e32 v183, 2, v162
	s_waitcnt lgkmcnt(0)
	v_pk_add_f32 v[60:61], v[60:61], v[74:75]
	ds_bpermute_b32 v75, v183, v61
	ds_bpermute_b32 v74, v183, v60
	v_cmp_lt_i32_e32 vcc, v163, v187
	v_mov_b32_e32 v32, 0
	s_movk_i32 s47, 0x4000
	v_cndmask_b32_e32 v162, v121, v163, vcc
	s_waitcnt lgkmcnt(0)
	v_pk_add_f32 v[60:61], v[60:61], v[74:75]
	v_cmp_lt_i32_e32 vcc, v186, v187
	v_log_f32_e32 v74, v61
	v_log_f32_e32 v75, v60
	v_cndmask_b32_e32 v163, v121, v186, vcc
	v_cmp_lt_f32_e32 vcc, 0, v61
	s_movk_i32 s43, 0x1000
	s_mov_b32 s33, 2
	v_cndmask_b32_e64 v186, 0, -v74, vcc
	v_cmp_lt_f32_e32 vcc, 0, v60
	s_not_b32 s39, s38
	v_add_u32_e32 v159, s42, v174
	v_add_u32_e32 v160, s42, v175
	v_add_u32_e32 v161, s42, v176
	v_mov_b32_e32 v33, v32
	v_mov_b32_e32 v34, v32
	v_mov_b32_e32 v35, v32
	v_mov_b32_e32 v36, v32
	v_mov_b32_e32 v37, v32
	v_mov_b32_e32 v38, v32
	v_mov_b32_e32 v39, v32
	v_mov_b32_e32 v40, v32
	v_mov_b32_e32 v41, v32
	v_mov_b32_e32 v42, v32
	v_mov_b32_e32 v43, v32
	v_mov_b32_e32 v44, v32
	v_mov_b32_e32 v45, v32
	v_mov_b32_e32 v46, v32
	v_mov_b32_e32 v47, v32
	v_mov_b32_e32 v48, v32
	v_mov_b32_e32 v49, v32
	v_mov_b32_e32 v50, v32
	v_mov_b32_e32 v51, v32
	v_mov_b32_e32 v52, v32
	v_mov_b32_e32 v53, v32
	v_mov_b32_e32 v54, v32
	v_mov_b32_e32 v55, v32
	v_mov_b32_e32 v56, v32
	v_mov_b32_e32 v57, v32
	v_mov_b32_e32 v58, v32
	v_mov_b32_e32 v59, v32
	v_lshlrev_b32_e32 v162, 2, v162
	v_lshlrev_b32_e32 v163, 2, v163
	v_cndmask_b32_e64 v187, 0, -v75, vcc
	v_mov_b32_e32 v60, v32
	v_mov_b32_e32 v61, v32
	v_readlane_b32 s50, v250, 56
	v_readlane_b32 s51, v250, 57
	s_waitcnt vmcnt(7)
	ds_write_b128 v127, v[62:65]
	s_waitcnt vmcnt(6)
	ds_write_b128 v127, v[66:69] offset:18432
	s_waitcnt vmcnt(5)
	ds_write_b128 v127, v[70:73] offset:4608
	s_waitcnt vmcnt(4)
	ds_write_b128 v127, v[188:191] offset:23040
	v_mov_b32_e32 v62, v32
	v_mov_b32_e32 v63, v32
	s_waitcnt lgkmcnt(0)
	s_barrier
	s_branch .LBB0_838

.LBB0_838:
	s_add_i32 s2, s33, -2
	s_and_b32 s40, s2, 1
	s_xor_b32 s2, s40, 1
	s_mulk_i32 s2, 0x2400
	s_min_i32 s41, s33, s38
	v_add_u32_e32 v64, s2, v127
	s_lshl_b32 s44, s41, 6
	s_lshl_b32 s2, s41, 7
	s_mov_b32 s3, s45
	s_waitcnt vmcnt(2)
	ds_write_b128 v64, v[20:23]
	ds_write_b128 v64, v[16:19] offset:18432
	s_waitcnt vmcnt(1)
	ds_write_b128 v64, v[24:27] offset:4608
	s_waitcnt vmcnt(0)
	ds_write_b128 v64, v[28:31] offset:23040
	v_lshl_add_u64 v[28:29], v[156:157], 0, s[2:3]
	s_lshl_b64 s[2:3], s[44:45], 7
	s_lshl_b32 s44, s41, 13
	v_lshl_add_u64 v[24:25], v[154:155], 0, s[44:45]
	v_add_co_u32_e32 v24, vcc, s43, v24
	v_lshl_add_u64 v[16:17], v[154:155], 0, s[2:3]
	s_nop 0
	v_addc_co_u32_e32 v25, vcc, 0, v25, vcc
	global_load_dwordx4 v[20:23], v[16:17], off
	s_nop 0
	global_load_dwordx4 v[16:19], v[28:29], off
	v_add_co_u32_e32 v28, vcc, s47, v28
	global_load_dwordx4 v[24:27], v[24:25], off
	s_nop 0
	v_addc_co_u32_e32 v29, vcc, 0, v29, vcc
	global_load_dwordx4 v[28:31], v[28:29], off
	s_mulk_i32 s40, 0x1200
	v_lshl_add_u32 v188, s40, 1, v129
	ds_read_b128 v[64:67], v188
	ds_read_b128 v[68:71], v188 offset:64
	s_waitcnt lgkmcnt(1)
	v_mfma_f32_16x16x32_bf16 v[72:75], v[64:67], v[0:3], 0
	v_cmp_le_i32_e32 vcc, v112, v113
	s_waitcnt lgkmcnt(0)
	v_mfma_f32_16x16x32_bf16 v[190:193], v[68:71], v[4:7], v[72:75]
	v_mfma_f32_16x16x32_bf16 v[64:67], v[64:67], v[8:11], 0
	v_mfma_f32_16x16x32_bf16 v[68:71], v[68:71], v[12:15], v[64:67]
	s_nop 5
	v_add_f32_e32 v189, v186, v190
	ds_read_b128 v[64:67], v188 offset:2304
	ds_read_b128 v[194:197], v188 offset:2368
	v_exp_f32_e32 v189, v189
	v_add_f32_e32 v190, v186, v191
	v_exp_f32_e32 v190, v190
	v_add_f32_e32 v191, v186, v192
	v_exp_f32_e32 v191, v191
	v_add_f32_e32 v192, v186, v193
	v_exp_f32_e32 v192, v192
	s_waitcnt lgkmcnt(1)
	v_mfma_f32_16x16x32_bf16 v[72:75], v[64:67], v[0:3], 0
	v_cndmask_b32_e32 v189, 0, v189, vcc
	v_cmp_lt_i32_e32 vcc, v112, v113
	v_mfma_f32_16x16x32_bf16 v[64:67], v[64:67], v[8:11], 0
	s_nop 0
	v_cndmask_b32_e32 v190, 0, v190, vcc
	v_cmp_le_i32_e32 vcc, v86, v113
	v_add_f32_e32 v193, v189, v190
	s_waitcnt lgkmcnt(0)
	v_mfma_f32_16x16x32_bf16 v[72:75], v[194:197], v[4:7], v[72:75]
	v_cndmask_b32_e32 v191, 0, v191, vcc
	v_cmp_le_i32_e32 vcc, v88, v113
	v_add_f32_e32 v193, v191, v193
	v_mfma_f32_16x16x32_bf16 v[64:67], v[194:197], v[12:15], v[64:67]
	v_cndmask_b32_e32 v192, 0, v192, vcc
	v_mul_f32_e32 v195, 0.5, v192
	v_fmac_f32_e32 v193, 0.5, v192
	s_nop 1
	v_mov_b32_dpp v194, v193 quad_perm:[1,0,3,2] row_mask:0xf bank_mask:0xf
	v_mov_b32_dpp v195, v195 quad_perm:[1,0,3,2] row_mask:0xf bank_mask:0xf
	s_waitcnt lgkmcnt(1)
	v_add_f32_e32 v193, v193, v194
	s_waitcnt lgkmcnt(0)
	v_fmac_f32_e32 v195, 0.5, v192
	s_nop 1
	v_mov_b32_dpp v194, v193 quad_perm:[2,3,0,1] row_mask:0xf bank_mask:0xf
	v_mov_b32_dpp v196, v195 quad_perm:[2,3,0,1] row_mask:0xf bank_mask:0xf
	s_and_saveexec_b64 s[2:3], s[4:5]
	s_cbranch_execz .LBB0_840
	s_waitcnt lgkmcnt(1)
	v_add_f32_e32 v193, v193, v194
	s_waitcnt lgkmcnt(0)
	v_add_f32_e32 v194, v195, v196
	ds_write_b32 v161, v193
	ds_write_b32 v160, v194
.LBB0_840:
	s_or_b64 exec, exec, s[2:3]
	v_add_f32_e32 v72, v186, v72
	v_exp_f32_e32 v72, v72
	v_add_f32_e32 v73, v186, v73
	v_exp_f32_e32 v73, v73
	v_cmp_le_i32_e32 vcc, v90, v113
	s_nop 1
	v_cndmask_b32_e32 v193, 0, v72, vcc
	v_cmp_le_i32_e32 vcc, v92, v113
	v_add_f32_e32 v72, v186, v74
	v_exp_f32_e32 v72, v72
	s_waitcnt lgkmcnt(1)
	v_cndmask_b32_e32 v194, 0, v73, vcc
	v_add_f32_e32 v73, v186, v75
	v_exp_f32_e32 v73, v73
	v_cmp_le_i32_e32 vcc, v94, v113
	s_nop 1
	v_cndmask_b32_e32 v195, 0, v72, vcc
	v_cmp_le_i32_e32 vcc, v96, v113
	v_add_f32_e32 v72, v193, v194
	s_waitcnt lgkmcnt(0)
	v_cndmask_b32_e32 v196, 0, v73, vcc
	v_add_f32_e32 v73, v195, v72
	v_fmac_f32_e32 v73, 0.5, v196
	v_mul_f32_e32 v72, 0.5, v196
	s_nop 1
	v_mov_b32_dpp v74, v73 quad_perm:[1,0,3,2] row_mask:0xf bank_mask:0xf
	v_mov_b32_dpp v72, v72 quad_perm:[1,0,3,2] row_mask:0xf bank_mask:0xf
	s_waitcnt lgkmcnt(1)
	v_add_f32_e32 v73, v73, v74
	s_waitcnt lgkmcnt(0)
	v_fmac_f32_e32 v72, 0.5, v196
	s_nop 1
	v_mov_b32_dpp v74, v73 quad_perm:[2,3,0,1] row_mask:0xf bank_mask:0xf
	v_mov_b32_dpp v75, v72 quad_perm:[2,3,0,1] row_mask:0xf bank_mask:0xf
	s_and_saveexec_b64 s[2:3], s[4:5]
	s_cbranch_execz .LBB0_842
	s_waitcnt lgkmcnt(1)
	v_add_f32_e32 v73, v73, v74
	s_waitcnt lgkmcnt(0)
	v_add_f32_e32 v72, v72, v75
	ds_write_b32 v161, v73 offset:16
	ds_write_b32 v160, v72 offset:16
.LBB0_842:
	s_or_b64 exec, exec, s[2:3]
	v_add_f32_e32 v68, v187, v68
	v_exp_f32_e32 v68, v68
	v_add_f32_e32 v69, v187, v69
	v_exp_f32_e32 v69, v69
	v_cmp_le_i32_e32 vcc, v112, v158
	s_nop 1
	v_cndmask_b32_e32 v72, 0, v68, vcc
	v_cmp_lt_i32_e32 vcc, v112, v158
	v_add_f32_e32 v68, v187, v70
	v_exp_f32_e32 v68, v68
	v_cndmask_b32_e32 v73, 0, v69, vcc
	v_add_f32_e32 v69, v187, v71
	v_exp_f32_e32 v69, v69
	v_cmp_le_i32_e32 vcc, v86, v158
	v_cvt_pk_bf16_f32 v71, v195, v196
	s_waitcnt lgkmcnt(1)
	s_nop 0
	v_cndmask_b32_e32 v74, 0, v68, vcc
	v_cmp_le_i32_e32 vcc, v88, v158
	v_add_f32_e32 v68, v72, v73
	v_add_f32_e32 v68, v74, v68
	s_waitcnt lgkmcnt(0)
	v_cndmask_b32_e32 v75, 0, v69, vcc
	v_fmac_f32_e32 v68, 0.5, v75
	v_mul_f32_e32 v70, 0.5, v75
	s_nop 1
	v_mov_b32_dpp v69, v68 quad_perm:[1,0,3,2] row_mask:0xf bank_mask:0xf
	v_mov_b32_dpp v197, v70 quad_perm:[1,0,3,2] row_mask:0xf bank_mask:0xf
	v_cvt_pk_bf16_f32 v70, v193, v194
	s_waitcnt lgkmcnt(1)
	v_add_f32_e32 v198, v68, v69
	s_waitcnt lgkmcnt(0)
	v_fmac_f32_e32 v197, 0.5, v75
	s_nop 1
	v_mov_b32_dpp v199, v198 quad_perm:[2,3,0,1] row_mask:0xf bank_mask:0xf
	v_mov_b32_dpp v200, v197 quad_perm:[2,3,0,1] row_mask:0xf bank_mask:0xf
	v_cvt_pk_bf16_f32 v68, v189, v190
	v_cvt_pk_bf16_f32 v69, v191, v192
	s_and_saveexec_b64 s[2:3], s[4:5]
	s_cbranch_execz .LBB0_844
	s_waitcnt lgkmcnt(1)
	v_add_f32_e32 v189, v198, v199
	s_waitcnt lgkmcnt(0)
	v_add_f32_e32 v190, v197, v200
	ds_write_b32 v159, v189
	ds_write_b32 v160, v190 offset:1040
.LBB0_844:
	s_or_b64 exec, exec, s[2:3]
	v_add_f32_e32 v64, v187, v64
	v_exp_f32_e32 v64, v64
	v_add_f32_e32 v65, v187, v65
	v_exp_f32_e32 v65, v65
	v_add_f32_e32 v66, v187, v66
	v_exp_f32_e32 v66, v66
	v_add_f32_e32 v67, v187, v67
	v_cmp_le_i32_e32 vcc, v90, v158
	v_exp_f32_e32 v67, v67
	s_nop 0
	v_cndmask_b32_e32 v64, 0, v64, vcc
	v_cmp_le_i32_e32 vcc, v92, v158
	s_nop 1
	v_cndmask_b32_e32 v65, 0, v65, vcc
	v_cmp_le_i32_e32 vcc, v94, v158
	v_add_f32_e32 v189, v64, v65
	s_nop 0
	v_cndmask_b32_e32 v66, 0, v66, vcc
	v_cmp_le_i32_e32 vcc, v96, v158
	v_add_f32_e32 v190, v66, v189
	s_nop 0
	v_cndmask_b32_e32 v67, 0, v67, vcc
	v_fmac_f32_e32 v190, 0.5, v67
	v_mul_f32_e32 v189, 0.5, v67
	s_nop 1
	v_mov_b32_dpp v191, v190 quad_perm:[1,0,3,2] row_mask:0xf bank_mask:0xf
	v_mov_b32_dpp v189, v189 quad_perm:[1,0,3,2] row_mask:0xf bank_mask:0xf
	s_waitcnt lgkmcnt(1)
	v_add_f32_e32 v190, v190, v191
	s_waitcnt lgkmcnt(0)
	v_fmac_f32_e32 v189, 0.5, v67
	s_nop 1
	v_mov_b32_dpp v191, v190 quad_perm:[2,3,0,1] row_mask:0xf bank_mask:0xf
	v_mov_b32_dpp v192, v189 quad_perm:[2,3,0,1] row_mask:0xf bank_mask:0xf
	s_and_saveexec_b64 s[2:3], s[4:5]
	s_cbranch_execz .LBB0_846
	s_waitcnt lgkmcnt(1)
	v_add_f32_e32 v190, v190, v191
	s_waitcnt lgkmcnt(0)
	v_add_f32_e32 v189, v189, v192
	ds_write_b32 v159, v190 offset:16
	ds_write_b32 v160, v189 offset:1056
.LBB0_846:
	s_or_b64 exec, exec, s[2:3]
	v_lshl_add_u32 v190, s40, 1, v131
	v_add_u32_e32 v189, 0x4800, v190
	v_cvt_pk_bf16_f32 v72, v72, v73
	v_cvt_pk_bf16_f32 v73, v74, v75
	v_cvt_pk_bf16_f32 v74, v64, v65
	v_cvt_pk_bf16_f32 v75, v66, v67
	ds_read2_b64 v[64:67], v189 offset1:4
	s_waitcnt lgkmcnt(2)
	v_add_u32_e32 v191, 0x5000, v190
	s_waitcnt lgkmcnt(1)
	v_add_u32_e32 v192, 0x5800, v190
	v_add_u32_e32 v190, 0x6000, v190
	v_cmp_le_i32_e32 vcc, v98, v113
	s_waitcnt lgkmcnt(0)
	v_mfma_f32_16x16x32_bf16 v[60:63], v[64:67], v[68:71], v[60:63]
	v_mfma_f32_16x16x32_bf16 v[44:47], v[64:67], v[72:75], v[44:47]
	ds_read2_b64 v[64:67], v191 offset0:32 offset1:36
	s_waitcnt lgkmcnt(0)
	v_mfma_f32_16x16x32_bf16 v[56:59], v[64:67], v[68:71], v[56:59]
	v_mfma_f32_16x16x32_bf16 v[40:43], v[64:67], v[72:75], v[40:43]
	ds_read2_b64 v[64:67], v192 offset0:64 offset1:68
	s_waitcnt lgkmcnt(0)
	v_mfma_f32_16x16x32_bf16 v[52:55], v[64:67], v[68:71], v[52:55]
	v_mfma_f32_16x16x32_bf16 v[36:39], v[64:67], v[72:75], v[36:39]
	ds_read2_b64 v[64:67], v190 offset0:96 offset1:100
	s_waitcnt lgkmcnt(0)
	v_mfma_f32_16x16x32_bf16 v[48:51], v[64:67], v[68:71], v[48:51]
	v_mfma_f32_16x16x32_bf16 v[32:35], v[64:67], v[72:75], v[32:35]
	ds_read_b128 v[64:67], v188 offset:4608
	ds_read_b128 v[68:71], v188 offset:4672
	s_waitcnt lgkmcnt(1)
	v_mfma_f32_16x16x32_bf16 v[72:75], v[64:67], v[0:3], 0
	s_waitcnt lgkmcnt(0)
	v_mfma_f32_16x16x32_bf16 v[194:197], v[68:71], v[4:7], v[72:75]
	v_mfma_f32_16x16x32_bf16 v[64:67], v[64:67], v[8:11], 0
	v_mfma_f32_16x16x32_bf16 v[68:71], v[68:71], v[12:15], v[64:67]
	s_nop 6
	ds_read_b128 v[64:67], v188 offset:6912
	ds_read_b128 v[198:201], v188 offset:6976
	v_add_f32_e32 v188, v186, v194
	v_exp_f32_e32 v188, v188
	v_add_f32_e32 v193, v186, v195
	v_exp_f32_e32 v193, v193
	v_add_f32_e32 v194, v186, v196
	v_exp_f32_e32 v194, v194
	v_add_f32_e32 v195, v186, v197
	v_exp_f32_e32 v195, v195
	s_waitcnt lgkmcnt(1)
	v_mfma_f32_16x16x32_bf16 v[72:75], v[64:67], v[0:3], 0
	v_cndmask_b32_e32 v188, 0, v188, vcc
	v_cmp_le_i32_e32 vcc, v100, v113
	v_mfma_f32_16x16x32_bf16 v[64:67], v[64:67], v[8:11], 0
	s_nop 0
	v_cndmask_b32_e32 v193, 0, v193, vcc
	v_cmp_le_i32_e32 vcc, v102, v113
	v_add_f32_e32 v196, v188, v193
	s_waitcnt lgkmcnt(0)
	v_mfma_f32_16x16x32_bf16 v[72:75], v[198:201], v[4:7], v[72:75]
	v_cndmask_b32_e32 v194, 0, v194, vcc
	v_cmp_le_i32_e32 vcc, v120, v113
	v_add_f32_e32 v196, v194, v196
	v_mfma_f32_16x16x32_bf16 v[64:67], v[198:201], v[12:15], v[64:67]
	v_cndmask_b32_e32 v195, 0, v195, vcc
	v_mul_f32_e32 v198, 0.5, v195
	v_fmac_f32_e32 v196, 0.5, v195
	s_nop 1
	v_mov_b32_dpp v197, v196 quad_perm:[1,0,3,2] row_mask:0xf bank_mask:0xf
	v_mov_b32_dpp v198, v198 quad_perm:[1,0,3,2] row_mask:0xf bank_mask:0xf
	s_waitcnt lgkmcnt(1)
	v_add_f32_e32 v196, v196, v197
	s_waitcnt lgkmcnt(0)
	v_fmac_f32_e32 v198, 0.5, v195
	s_nop 1
	v_mov_b32_dpp v197, v196 quad_perm:[2,3,0,1] row_mask:0xf bank_mask:0xf
	v_mov_b32_dpp v199, v198 quad_perm:[2,3,0,1] row_mask:0xf bank_mask:0xf
	s_and_saveexec_b64 s[2:3], s[4:5]
	s_cbranch_execz .LBB0_848
	s_waitcnt lgkmcnt(1)
	v_add_f32_e32 v196, v196, v197
	s_waitcnt lgkmcnt(0)
	v_add_f32_e32 v197, v198, v199
	ds_write_b32 v161, v196 offset:32
	ds_write_b32 v160, v197 offset:32
.LBB0_848:
	s_or_b64 exec, exec, s[2:3]
	v_add_f32_e32 v72, v186, v72
	v_exp_f32_e32 v72, v72
	v_add_f32_e32 v73, v186, v73
	v_cmp_le_i32_e32 vcc, v122, v113
	v_exp_f32_e32 v196, v73
	s_nop 0
	v_cndmask_b32_e32 v73, 0, v72, vcc
	v_add_f32_e32 v72, v186, v74
	v_exp_f32_e32 v72, v72
	v_add_f32_e32 v74, v186, v75
	v_exp_f32_e32 v74, v74
	v_cmp_le_i32_e32 vcc, v124, v113
	s_nop 1
	v_cndmask_b32_e32 v196, 0, v196, vcc
	v_cmp_le_i32_e32 vcc, v126, v113
	s_waitcnt lgkmcnt(1)
	s_nop 0
	v_cndmask_b32_e32 v197, 0, v72, vcc
	v_cmp_le_i32_e32 vcc, v128, v113
	v_add_f32_e32 v72, v73, v196
	s_waitcnt lgkmcnt(0)
	v_cndmask_b32_e32 v199, 0, v74, vcc
	v_add_f32_e32 v74, v197, v72
	v_fmac_f32_e32 v74, 0.5, v199
	v_mul_f32_e32 v72, 0.5, v199
	s_nop 1
	v_mov_b32_dpp v75, v74 quad_perm:[1,0,3,2] row_mask:0xf bank_mask:0xf
	v_mov_b32_dpp v72, v72 quad_perm:[1,0,3,2] row_mask:0xf bank_mask:0xf
	s_waitcnt lgkmcnt(1)
	v_add_f32_e32 v74, v74, v75
	s_waitcnt lgkmcnt(0)
	v_fmac_f32_e32 v72, 0.5, v199
	s_nop 1
	v_mov_b32_dpp v75, v74 quad_perm:[2,3,0,1] row_mask:0xf bank_mask:0xf
	v_mov_b32_dpp v198, v72 quad_perm:[2,3,0,1] row_mask:0xf bank_mask:0xf
	s_and_saveexec_b64 s[2:3], s[4:5]
	s_cbranch_execz .LBB0_850
	s_waitcnt lgkmcnt(1)
	v_add_f32_e32 v74, v74, v75
	s_waitcnt lgkmcnt(0)
	v_add_f32_e32 v72, v72, v198
	ds_write_b32 v161, v74 offset:48
	ds_write_b32 v160, v72 offset:48
.LBB0_850:
	s_or_b64 exec, exec, s[2:3]
	v_add_f32_e32 v68, v187, v68
	v_exp_f32_e32 v68, v68
	v_add_f32_e32 v69, v187, v69
	v_exp_f32_e32 v69, v69
	v_cmp_le_i32_e32 vcc, v98, v158
	s_nop 1
	v_cndmask_b32_e32 v72, 0, v68, vcc
	v_cmp_le_i32_e32 vcc, v100, v158
	v_add_f32_e32 v68, v187, v70
	v_exp_f32_e32 v68, v68
	v_cndmask_b32_e32 v74, 0, v69, vcc
	v_add_f32_e32 v69, v187, v71
	v_exp_f32_e32 v69, v69
	v_cmp_le_i32_e32 vcc, v102, v158
	v_cvt_pk_bf16_f32 v71, v197, v199
	s_waitcnt lgkmcnt(1)
	s_nop 0
	v_cndmask_b32_e32 v75, 0, v68, vcc
	v_cmp_le_i32_e32 vcc, v120, v158
	v_add_f32_e32 v68, v72, v74
	v_add_f32_e32 v68, v75, v68
	s_waitcnt lgkmcnt(0)
	v_cndmask_b32_e32 v198, 0, v69, vcc
	v_fmac_f32_e32 v68, 0.5, v198
	v_mul_f32_e32 v70, 0.5, v198
	s_nop 1
	v_mov_b32_dpp v69, v68 quad_perm:[1,0,3,2] row_mask:0xf bank_mask:0xf
	v_mov_b32_dpp v200, v70 quad_perm:[1,0,3,2] row_mask:0xf bank_mask:0xf
	v_cvt_pk_bf16_f32 v70, v73, v196
	s_waitcnt lgkmcnt(1)
	v_add_f32_e32 v201, v68, v69
	s_waitcnt lgkmcnt(0)
	v_fmac_f32_e32 v200, 0.5, v198
	s_nop 1
	v_mov_b32_dpp v202, v201 quad_perm:[2,3,0,1] row_mask:0xf bank_mask:0xf
	v_mov_b32_dpp v203, v200 quad_perm:[2,3,0,1] row_mask:0xf bank_mask:0xf
	v_cvt_pk_bf16_f32 v68, v188, v193
	v_cvt_pk_bf16_f32 v69, v194, v195
	s_and_saveexec_b64 s[2:3], s[4:5]
	s_cbranch_execz .LBB0_852
	s_waitcnt lgkmcnt(1)
	v_add_f32_e32 v73, v201, v202
	s_waitcnt lgkmcnt(0)
	v_add_f32_e32 v188, v200, v203
	ds_write_b32 v159, v73 offset:32
	ds_write_b32 v160, v188 offset:1072
.LBB0_852:
	s_or_b64 exec, exec, s[2:3]
	v_add_f32_e32 v64, v187, v64
	v_exp_f32_e32 v64, v64
	v_add_f32_e32 v65, v187, v65
	v_exp_f32_e32 v65, v65
	v_add_f32_e32 v66, v187, v66
	v_exp_f32_e32 v66, v66
	v_add_f32_e32 v67, v187, v67
	v_cmp_le_i32_e32 vcc, v122, v158
	v_exp_f32_e32 v67, v67
	s_nop 0
	v_cndmask_b32_e32 v64, 0, v64, vcc
	v_cmp_le_i32_e32 vcc, v124, v158
	s_nop 1
	v_cndmask_b32_e32 v65, 0, v65, vcc
	v_cmp_le_i32_e32 vcc, v126, v158
	v_add_f32_e32 v73, v64, v65
	s_nop 0
	v_cndmask_b32_e32 v66, 0, v66, vcc
	v_cmp_le_i32_e32 vcc, v128, v158
	v_add_f32_e32 v188, v66, v73
	s_nop 0
	v_cndmask_b32_e32 v67, 0, v67, vcc
	v_fmac_f32_e32 v188, 0.5, v67
	v_mul_f32_e32 v73, 0.5, v67
	s_nop 1
	v_mov_b32_dpp v193, v188 quad_perm:[1,0,3,2] row_mask:0xf bank_mask:0xf
	v_mov_b32_dpp v73, v73 quad_perm:[1,0,3,2] row_mask:0xf bank_mask:0xf
	s_waitcnt lgkmcnt(1)
	v_add_f32_e32 v188, v188, v193
	s_waitcnt lgkmcnt(0)
	v_fmac_f32_e32 v73, 0.5, v67
	s_nop 1
	v_mov_b32_dpp v193, v188 quad_perm:[2,3,0,1] row_mask:0xf bank_mask:0xf
	v_mov_b32_dpp v194, v73 quad_perm:[2,3,0,1] row_mask:0xf bank_mask:0xf
	s_and_saveexec_b64 s[2:3], s[4:5]
	s_cbranch_execz .LBB0_837
	s_waitcnt lgkmcnt(1)
	v_add_f32_e32 v188, v188, v193
	s_waitcnt lgkmcnt(0)
	v_add_f32_e32 v73, v73, v194
	ds_write_b32 v159, v188 offset:48
	ds_write_b32 v160, v73 offset:1088
	s_branch .LBB0_837

.LBB0_870:
	v_readlane_b32 s48, v250, 24
	v_readlane_b32 s52, v250, 28
	v_readlane_b32 s53, v250, 29
	s_add_u32 s2, s52, s42
	s_addc_u32 s3, s53, 0
	s_add_u32 s2, s2, s40
	s_addc_u32 s3, s3, s41
	s_waitcnt vmcnt(2)
	v_lshl_add_u64 v[48:49], s[2:3], 0, v[84:85]
	s_lshl_b32 s44, s33, 6
	s_lshl_b32 s2, s33, 7
	s_mov_b32 s3, s45
	s_waitcnt vmcnt(1)
	v_lshl_add_u64 v[58:59], v[48:49], 0, v[116:117]
	s_waitcnt vmcnt(0)
	v_lshl_add_u64 v[62:63], v[156:157], 0, s[2:3]
	s_lshl_b64 s[2:3], s[44:45], 7
	v_lshl_add_u64 v[48:49], v[58:59], 0, s[2:3]
	s_lshl_b32 s2, s33, 13
	s_mov_b32 s3, s45
	v_lshl_add_u64 v[58:59], v[58:59], 0, s[2:3]
	s_movk_i32 s2, 0x1000
	v_add_co_u32_e32 v58, vcc, s2, v58
	global_load_dwordx4 v[48:51], v[48:49], off
	s_nop 0
	global_load_dwordx4 v[54:57], v[62:63], off
	v_addc_co_u32_e32 v59, vcc, 0, v59, vcc
	s_mov_b32 s2, 0x40000
	v_add_co_u32_e32 v62, vcc, s2, v62
	global_load_dwordx4 v[58:61], v[58:59], off
	s_nop 0
	v_addc_co_u32_e32 v63, vcc, 0, v63, vcc
	global_load_dwordx4 v[62:65], v[62:63], off
	v_lshrrev_b64 v[70:71], s33, v[72:73]
	v_lshrrev_b64 v[72:73], s33, v[74:75]
	s_mov_b32 s42, 0
	v_readlane_b32 s49, v250, 25
	v_readlane_b32 s50, v250, 26
	v_readlane_b32 s51, v250, 27
	v_readlane_b32 s54, v250, 30
	v_readlane_b32 s55, v250, 31
	v_readlane_b32 s56, v250, 32
	v_readlane_b32 s57, v250, 33
	v_readlane_b32 s58, v250, 34
	v_readlane_b32 s59, v250, 35
	v_readlane_b32 s60, v250, 36
	v_readlane_b32 s61, v250, 37
	v_readlane_b32 s62, v250, 38
	v_readlane_b32 s63, v250, 39
	s_waitcnt vmcnt(3)
	ds_write_b128 v127, v[48:51]
	s_waitcnt vmcnt(2)
	ds_write_b128 v127, v[54:57] offset:18432
	s_waitcnt vmcnt(1)
	ds_write_b128 v127, v[58:61] offset:4608
	s_waitcnt vmcnt(0)
	ds_write_b128 v127, v[62:65] offset:23040
	s_waitcnt lgkmcnt(0)
	s_barrier
	ds_write_b128 v127, v[48:51] offset:9216
	ds_write_b128 v127, v[54:57] offset:27648
	ds_write_b128 v127, v[58:61] offset:13824
	ds_write_b128 v127, v[62:65] offset:32256
	ds_read_b128 v[48:51], v129
	ds_read_b128 v[54:57], v129 offset:64
	s_waitcnt lgkmcnt(1)
	v_mfma_f32_16x16x32_bf16 v[58:61], v[48:51], v[0:3], 0
	v_mfma_f32_16x16x32_bf16 v[48:51], v[48:51], v[8:11], 0
	s_waitcnt lgkmcnt(0)
	v_mfma_f32_16x16x32_bf16 v[58:61], v[54:57], v[4:7], v[58:61]
	v_mfma_f32_16x16x32_bf16 v[48:51], v[54:57], v[12:15], v[48:51]
	ds_read_b128 v[54:57], v129 offset:2304
	ds_read_b128 v[62:65], v129 offset:2368
	s_nop 4
	v_exp_f32_e32 v58, v58
	v_exp_f32_e32 v59, v59
	s_waitcnt lgkmcnt(1)
	v_mfma_f32_16x16x32_bf16 v[66:69], v[54:57], v[0:3], 0
	v_exp_f32_e32 v48, v48
	v_exp_f32_e32 v49, v49
	v_exp_f32_e32 v60, v60
	v_mfma_f32_16x16x32_bf16 v[54:57], v[54:57], v[8:11], 0
	v_exp_f32_e32 v50, v50
	v_exp_f32_e32 v51, v51
	v_exp_f32_e32 v61, v61
	s_waitcnt lgkmcnt(0)
	v_mfma_f32_16x16x32_bf16 v[54:57], v[62:65], v[12:15], v[54:57]
	v_mfma_f32_16x16x32_bf16 v[66:69], v[62:65], v[4:7], v[66:69]
	v_subrev_u32_e32 v65, s44, v184
	v_bfe_i32 v63, v70, 0, 1
	v_subrev_u32_e32 v64, s44, v185
	v_cmp_le_i32_e32 vcc, v97, v65
	s_nop 2
	v_exp_f32_e32 v73, v54
	v_bfe_i32 v62, v72, 0, 1
	v_cndmask_b32_e32 v54, 0, v63, vcc
	v_cmp_le_i32_e32 vcc, v112, v64
	v_exp_f32_e32 v80, v56
	v_exp_f32_e32 v75, v55
	v_cndmask_b32_e32 v56, 0, v62, vcc
	v_cmp_lt_i32_e32 vcc, v112, v64
	v_and_b32_e32 v55, v54, v58
	v_and_b32_e32 v54, v56, v48
	v_cndmask_b32_e32 v56, 0, v62, vcc
	v_cmp_le_i32_e32 vcc, v99, v65
	v_cmp_lt_i32_e64 s[2:3], v97, v65
	v_and_b32_e32 v56, v56, v49
	v_cndmask_b32_e32 v49, 0, v63, vcc
	v_cmp_le_i32_e32 vcc, v86, v64
	v_cndmask_b32_e64 v48, 0, v63, s[2:3]
	v_exp_f32_e32 v66, v66
	v_cndmask_b32_e32 v58, 0, v62, vcc
	v_cmp_le_i32_e32 vcc, v101, v65
	v_exp_f32_e32 v113, v57
	v_and_b32_e32 v57, v48, v59
	v_and_b32_e32 v59, v49, v60
	v_cndmask_b32_e32 v49, 0, v63, vcc
	v_cmp_le_i32_e32 vcc, v88, v64
	v_and_b32_e32 v58, v58, v50
	v_exp_f32_e32 v74, v68
	v_cndmask_b32_e32 v50, 0, v62, vcc
	v_cmp_le_i32_e32 vcc, v103, v65
	v_and_b32_e32 v68, v50, v51
	v_exp_f32_e32 v67, v67
	v_cndmask_b32_e32 v50, 0, v63, vcc
	v_cmp_le_i32_e32 vcc, v90, v64
	v_and_b32_e32 v71, v50, v66
	v_pk_add_f32 v[52:53], v[52:53], v[54:55]
	v_cndmask_b32_e32 v51, 0, v62, vcc
	v_cmp_le_i32_e32 vcc, v105, v65
	v_and_b32_e32 v70, v51, v73
	v_pk_add_f32 v[52:53], v[52:53], v[56:57]
	v_cndmask_b32_e32 v50, 0, v63, vcc
	v_cmp_le_i32_e32 vcc, v92, v64
	v_exp_f32_e32 v76, v69
	v_and_b32_e32 v69, v49, v61
	v_cndmask_b32_e32 v51, 0, v62, vcc
	v_cmp_le_i32_e32 vcc, v107, v65
	v_and_b32_e32 v72, v51, v75
	v_pk_add_f32 v[52:53], v[52:53], v[58:59]
	v_cndmask_b32_e32 v51, 0, v63, vcc
	v_cmp_le_i32_e32 vcc, v94, v64
	v_cvt_pk_bf16_f32 v48, v55, v57
	v_pk_add_f32 v[52:53], v[52:53], v[68:69]
	v_and_b32_e32 v73, v50, v67
	v_cndmask_b32_e32 v55, 0, v62, vcc
	v_cmp_le_i32_e32 vcc, v95, v65
	v_pk_add_f32 v[52:53], v[52:53], v[70:71]
	v_and_b32_e32 v75, v51, v74
	v_cndmask_b32_e32 v51, 0, v63, vcc
	v_cmp_le_i32_e32 vcc, v96, v64
	v_pk_add_f32 v[52:53], v[52:53], v[72:73]
	v_and_b32_e32 v74, v55, v80
	v_cndmask_b32_e32 v55, 0, v62, vcc
	v_cvt_pk_bf16_f32 v49, v59, v69
	v_pk_add_f32 v[52:53], v[52:53], v[74:75]
	v_and_b32_e32 v157, v51, v76
	v_and_b32_e32 v156, v55, v113
	v_cvt_pk_bf16_f32 v51, v75, v157
	v_cvt_pk_bf16_f32 v69, v74, v156
	v_add_u32_e32 v74, 0x4800, v131
	v_add_u32_e32 v75, 0x5000, v131
	v_pk_add_f32 v[60:61], v[52:53], v[156:157]
	v_cvt_pk_bf16_f32 v66, v54, v56
	v_cvt_pk_bf16_f32 v67, v58, v68
	ds_read2_b64 v[52:55], v74 offset1:4
	ds_read2_b64 v[56:59], v75 offset0:32 offset1:36
	v_add_u32_e32 v76, 0x5800, v131
	v_cvt_pk_bf16_f32 v50, v71, v73
	v_cvt_pk_bf16_f32 v68, v70, v72
	v_add_u32_e32 v80, 0x6000, v131
	s_waitcnt lgkmcnt(1)
	v_mfma_f32_16x16x32_bf16 v[28:31], v[52:55], v[48:51], v[28:31]
	v_cmp_le_i32_e32 vcc, v100, v65
	v_mfma_f32_16x16x32_bf16 v[20:23], v[52:55], v[66:69], v[20:23]
	s_waitcnt lgkmcnt(0)
	v_mfma_f32_16x16x32_bf16 v[52:55], v[56:59], v[48:51], v[16:19]
	s_nop 2
	ds_read2_b64 v[16:19], v76 offset0:64 offset1:68
	v_mfma_f32_16x16x32_bf16 v[56:59], v[56:59], v[66:69], v[24:27]
	s_waitcnt lgkmcnt(0)
	v_mfma_f32_16x16x32_bf16 v[24:27], v[16:19], v[48:51], v[40:43]
	s_nop 2
	ds_read2_b64 v[40:43], v80 offset0:96 offset1:100
	v_mfma_f32_16x16x32_bf16 v[44:47], v[16:19], v[66:69], v[44:47]
	s_waitcnt lgkmcnt(0)
	v_mfma_f32_16x16x32_bf16 v[16:19], v[40:43], v[48:51], v[36:39]
	v_mfma_f32_16x16x32_bf16 v[48:51], v[40:43], v[66:69], v[32:35]
	s_nop 2
	ds_read_b128 v[32:35], v129 offset:4608
	ds_read_b128 v[36:39], v129 offset:4672
	s_waitcnt lgkmcnt(1)
	v_mfma_f32_16x16x32_bf16 v[40:43], v[32:35], v[0:3], 0
	v_mfma_f32_16x16x32_bf16 v[32:35], v[32:35], v[8:11], 0
	s_waitcnt lgkmcnt(0)
	v_mfma_f32_16x16x32_bf16 v[40:43], v[36:39], v[4:7], v[40:43]
	v_mfma_f32_16x16x32_bf16 v[32:35], v[36:39], v[12:15], v[32:35]
	ds_read_b128 v[36:39], v129 offset:6912
	ds_read_b128 v[66:69], v129 offset:6976
	s_nop 4
	v_exp_f32_e32 v40, v40
	v_exp_f32_e32 v42, v42
	s_waitcnt lgkmcnt(1)
	v_mfma_f32_16x16x32_bf16 v[70:73], v[36:39], v[0:3], 0
	v_exp_f32_e32 v32, v32
	v_exp_f32_e32 v34, v34
	v_mfma_f32_16x16x32_bf16 v[36:39], v[36:39], v[8:11], 0
	s_waitcnt lgkmcnt(0)
	v_mfma_f32_16x16x32_bf16 v[70:73], v[66:69], v[4:7], v[70:73]
	v_mfma_f32_16x16x32_bf16 v[36:39], v[66:69], v[12:15], v[36:39]
	v_cndmask_b32_e32 v67, 0, v63, vcc
	v_cmp_le_i32_e32 vcc, v93, v65
	v_exp_f32_e32 v66, v41
	v_exp_f32_e32 v68, v43
	v_cndmask_b32_e32 v41, 0, v63, vcc
	v_cmp_le_i32_e32 vcc, v98, v64
	v_and_b32_e32 v41, v41, v40
	s_nop 0
	v_exp_f32_e32 v36, v36
	v_cndmask_b32_e32 v43, 0, v62, vcc
	v_and_b32_e32 v40, v43, v32
	v_exp_f32_e32 v32, v33
	v_cmp_le_i32_e32 vcc, v100, v64
	v_and_b32_e32 v33, v67, v66
	v_exp_f32_e32 v69, v70
	v_cndmask_b32_e32 v43, 0, v62, vcc
	v_cmp_le_i32_e32 vcc, v102, v65
	v_and_b32_e32 v32, v43, v32
	v_exp_f32_e32 v113, v71
	v_cndmask_b32_e32 v43, 0, v63, vcc
	v_cmp_le_i32_e32 vcc, v102, v64
	v_and_b32_e32 v43, v43, v42
	v_exp_f32_e32 v72, v72
	v_cndmask_b32_e32 v67, 0, v62, vcc
	v_cmp_le_i32_e32 vcc, v79, v65
	v_and_b32_e32 v42, v67, v34
	v_exp_f32_e32 v34, v35
	v_cndmask_b32_e32 v35, 0, v63, vcc
	v_cmp_le_i32_e32 vcc, v120, v64
	v_and_b32_e32 v35, v35, v68
	v_exp_f32_e32 v38, v38
	v_cndmask_b32_e32 v67, 0, v62, vcc
	v_cmp_le_i32_e32 vcc, v83, v65
	v_pk_add_f32 v[60:61], v[60:61], v[40:41]
	v_exp_f32_e32 v153, v73
	v_cndmask_b32_e32 v68, 0, v63, vcc
	v_cmp_le_i32_e32 vcc, v122, v64
	v_and_b32_e32 v71, v68, v69
	v_pk_add_f32 v[60:61], v[60:61], v[32:33]
	v_cndmask_b32_e32 v70, 0, v62, vcc
	v_cmp_le_i32_e32 vcc, v87, v65
	v_and_b32_e32 v70, v70, v36
	v_exp_f32_e32 v36, v37
	v_cndmask_b32_e32 v37, 0, v63, vcc
	v_cmp_le_i32_e32 vcc, v124, v64
	v_and_b32_e32 v37, v37, v113
	v_and_b32_e32 v34, v67, v34
	v_cndmask_b32_e32 v68, 0, v62, vcc
	v_cmp_le_i32_e32 vcc, v89, v65
	v_pk_add_f32 v[60:61], v[60:61], v[42:43]
	v_and_b32_e32 v36, v68, v36
	v_cndmask_b32_e32 v69, 0, v63, vcc
	v_cmp_le_i32_e32 vcc, v126, v64
	v_and_b32_e32 v73, v69, v72
	v_pk_add_f32 v[60:61], v[60:61], v[34:35]
	v_cndmask_b32_e32 v113, 0, v62, vcc
	v_and_b32_e32 v72, v113, v38
	v_exp_f32_e32 v38, v39
	v_cmp_le_i32_e32 vcc, v91, v65
	v_pk_add_f32 v[60:61], v[60:61], v[70:71]
	v_cvt_pk_bf16_f32 v68, v71, v37
	v_cvt_pk_bf16_f32 v66, v41, v33
	v_cvt_pk_bf16_f32 v67, v43, v35
	s_nop 0
	v_cndmask_b32_e32 v39, 0, v63, vcc
	v_cmp_le_i32_e32 vcc, v128, v64
	v_pk_add_f32 v[60:61], v[60:61], v[36:37]
	v_and_b32_e32 v39, v39, v153
	v_cndmask_b32_e32 v62, 0, v62, vcc
	v_and_b32_e32 v38, v62, v38
	v_pk_add_f32 v[60:61], v[60:61], v[72:73]
	v_cvt_pk_bf16_f32 v69, v73, v39
	v_cvt_pk_bf16_f32 v62, v70, v36
	v_cvt_pk_bf16_f32 v63, v72, v38
	s_nop 0
	v_pk_add_f32 v[64:65], v[60:61], v[38:39]
	ds_read2_b64 v[36:39], v74 offset0:8 offset1:12
	v_cvt_pk_bf16_f32 v60, v40, v32
	v_cvt_pk_bf16_f32 v61, v42, v34
	s_waitcnt lgkmcnt(0)
	v_mfma_f32_16x16x32_bf16 v[32:35], v[36:39], v[66:69], v[28:31]
	s_nop 2
	ds_read2_b64 v[28:31], v75 offset0:40 offset1:44
	v_mfma_f32_16x16x32_bf16 v[20:23], v[36:39], v[60:63], v[20:23]
	s_waitcnt lgkmcnt(0)
	v_mfma_f32_16x16x32_bf16 v[36:39], v[28:31], v[66:69], v[52:55]
	s_nop 2
	ds_read2_b64 v[52:55], v76 offset0:72 offset1:76
	s_waitcnt lgkmcnt(0)
	v_mfma_f32_16x16x32_bf16 v[40:43], v[52:55], v[66:69], v[24:27]
	v_mfma_f32_16x16x32_bf16 v[24:27], v[52:55], v[60:63], v[44:47]
	ds_read2_b64 v[52:55], v80 offset0:104 offset1:108
	s_waitcnt lgkmcnt(0)
	s_barrier
	v_mfma_f32_16x16x32_bf16 v[44:47], v[52:55], v[66:69], v[16:19]
	v_mfma_f32_16x16x32_bf16 v[16:19], v[52:55], v[60:63], v[48:51]
	s_nop 2
	ds_bpermute_b32 v49, v182, v65
	ds_bpermute_b32 v48, v182, v64
	v_mfma_f32_16x16x32_bf16 v[28:31], v[28:31], v[60:63], v[56:59]
	v_mov_b32_e32 v63, 0
	v_mov_b32_e32 v62, v63
	v_mov_b32_e32 v61, v63
	s_waitcnt lgkmcnt(0)
	v_pk_add_f32 v[48:49], v[64:65], v[48:49]
	ds_bpermute_b32 v51, v183, v49
	ds_bpermute_b32 v50, v183, v48
	v_mov_b32_e32 v60, v63
	v_mov_b32_e32 v59, v63
	v_mov_b32_e32 v156, v63
	v_mov_b32_e32 v153, v63
	s_waitcnt lgkmcnt(0)
	v_pk_add_f32 v[48:49], v[48:49], v[50:51]
	s_nop 0
	v_div_scale_f32 v50, s[2:3], v49, v49, v81
	v_rcp_f32_e32 v51, v50
	v_cmp_lt_f32_e64 s[2:3], 0, v48
	v_fma_f32 v52, -v50, v51, 1.0
	v_fmac_f32_e32 v51, v52, v51
	v_div_scale_f32 v52, vcc, v81, v49, v81
	v_mul_f32_e32 v53, v52, v51
	v_fma_f32 v54, -v50, v53, v52
	v_fmac_f32_e32 v53, v54, v51
	v_fma_f32 v50, -v50, v53, v52
	v_div_fmas_f32 v50, v50, v51, v53
	v_div_fixup_f32 v50, v50, v49, v81
	v_cmp_lt_f32_e32 vcc, 0, v49
	s_nop 1
	v_cndmask_b32_e32 v49, 0, v50, vcc
	v_div_scale_f32 v50, s[46:47], v48, v48, v77
	v_rcp_f32_e32 v51, v50
	v_readlane_b32 s47, v248, 14
	v_fma_f32 v52, -v50, v51, 1.0
	v_fmac_f32_e32 v51, v52, v51
	v_div_scale_f32 v52, vcc, v77, v48, v77
	v_mul_f32_e32 v53, v52, v51
	v_fma_f32 v54, -v50, v53, v52
	v_fmac_f32_e32 v53, v54, v51
	v_fma_f32 v50, -v50, v53, v52
	v_div_fmas_f32 v50, v50, v51, v53
	v_div_fixup_f32 v48, v50, v48, v77
	global_load_dwordx2 v[50:51], v[154:155], off
	global_load_dwordx2 v[52:53], v[154:155], off offset:32
	global_load_dwordx2 v[54:55], v[154:155], off offset:64
	global_load_dwordx2 v[56:57], v[154:155], off offset:96
	v_cndmask_b32_e64 v48, 0, v48, s[2:3]
	v_readlane_b32 s2, v248, 16
	s_addk_i32 s2, 0xfe01
	s_ashr_i32 s2, s2, 6
	s_cmpk_lt_u32 s47, 0xe0
	s_cselect_b32 s44, s2, 0
	s_cmp_gt_i32 s44, s33
	s_waitcnt vmcnt(3)
	v_lshlrev_b32_e32 v58, 16, v50
	v_fmac_f32_e32 v58, v32, v49
	v_and_b32_e32 v32, 0xffff0000, v50
	v_fmac_f32_e32 v32, v33, v49
	v_lshlrev_b32_e32 v33, 16, v51
	v_fmac_f32_e32 v33, v34, v49
	v_and_b32_e32 v34, 0xffff0000, v51
	v_fmac_f32_e32 v34, v35, v49
	v_cvt_pk_bf16_f32 v32, v58, v32
	v_cvt_pk_bf16_f32 v33, v33, v34
	global_store_dwordx2 v[154:155], v[32:33], off
	s_waitcnt vmcnt(3)
	v_lshlrev_b32_e32 v32, 16, v52
	v_and_b32_e32 v33, 0xffff0000, v52
	v_fmac_f32_e32 v32, v36, v49
	v_fmac_f32_e32 v33, v37, v49
	v_lshlrev_b32_e32 v34, 16, v53
	v_and_b32_e32 v35, 0xffff0000, v53
	v_fmac_f32_e32 v34, v38, v49
	v_fmac_f32_e32 v35, v39, v49
	v_cvt_pk_bf16_f32 v32, v32, v33
	v_cvt_pk_bf16_f32 v33, v34, v35
	global_store_dwordx2 v[154:155], v[32:33], off offset:32
	s_waitcnt vmcnt(3)
	v_lshlrev_b32_e32 v32, 16, v54
	v_and_b32_e32 v33, 0xffff0000, v54
	v_fmac_f32_e32 v32, v40, v49
	v_fmac_f32_e32 v33, v41, v49
	v_lshlrev_b32_e32 v34, 16, v55
	v_and_b32_e32 v35, 0xffff0000, v55
	v_fmac_f32_e32 v34, v42, v49
	v_fmac_f32_e32 v35, v43, v49
	v_cvt_pk_bf16_f32 v32, v32, v33
	v_cvt_pk_bf16_f32 v33, v34, v35
	global_store_dwordx2 v[154:155], v[32:33], off offset:64
	s_waitcnt vmcnt(3)
	v_lshlrev_b32_e32 v32, 16, v56
	v_and_b32_e32 v33, 0xffff0000, v56
	v_fmac_f32_e32 v32, v44, v49
	v_fmac_f32_e32 v33, v45, v49
	v_lshlrev_b32_e32 v34, 16, v57
	v_and_b32_e32 v35, 0xffff0000, v57
	v_fmac_f32_e32 v34, v46, v49
	v_fmac_f32_e32 v35, v47, v49
	v_cvt_pk_bf16_f32 v32, v32, v33
	v_cvt_pk_bf16_f32 v33, v34, v35
	global_store_dwordx2 v[154:155], v[32:33], off offset:96
	global_load_dwordx2 v[32:33], v[150:151], off
	s_nop 0
	global_load_dwordx2 v[34:35], v[150:151], off offset:32
	global_load_dwordx2 v[36:37], v[150:151], off offset:64
	global_load_dwordx2 v[38:39], v[150:151], off offset:96
	v_mov_b32_e32 v58, v63
	v_mov_b32_e32 v57, v63
	v_mov_b32_e32 v56, v63
	v_mov_b32_e32 v55, v63
	v_mov_b32_e32 v54, v63
	v_mov_b32_e32 v53, v63
	v_mov_b32_e32 v52, v63
	s_waitcnt vmcnt(3)
	v_lshlrev_b32_e32 v40, 16, v32
	v_fmac_f32_e32 v40, v20, v48
	v_and_b32_e32 v20, 0xffff0000, v32
	v_fmac_f32_e32 v20, v21, v48
	v_lshlrev_b32_e32 v21, 16, v33
	v_fmac_f32_e32 v21, v22, v48
	v_and_b32_e32 v22, 0xffff0000, v33
	v_cvt_pk_bf16_f32 v20, v40, v20
	v_fmac_f32_e32 v22, v23, v48
	v_cvt_pk_bf16_f32 v21, v21, v22
	global_store_dwordx2 v[150:151], v[20:21], off
	s_waitcnt vmcnt(3)
	v_lshlrev_b32_e32 v20, 16, v34
	v_fmac_f32_e32 v20, v28, v48
	v_and_b32_e32 v21, 0xffff0000, v34
	v_fmac_f32_e32 v21, v29, v48
	v_lshlrev_b32_e32 v22, 16, v35
	v_and_b32_e32 v23, 0xffff0000, v35
	v_cvt_pk_bf16_f32 v20, v20, v21
	v_fmac_f32_e32 v22, v30, v48
	v_fmac_f32_e32 v23, v31, v48
	v_cvt_pk_bf16_f32 v21, v22, v23
	global_store_dwordx2 v[150:151], v[20:21], off offset:32
	s_waitcnt vmcnt(3)
	v_lshlrev_b32_e32 v20, 16, v36
	v_fmac_f32_e32 v20, v24, v48
	v_and_b32_e32 v21, 0xffff0000, v36
	v_fmac_f32_e32 v21, v25, v48
	v_lshlrev_b32_e32 v22, 16, v37
	v_and_b32_e32 v23, 0xffff0000, v37
	v_cvt_pk_bf16_f32 v20, v20, v21
	v_fmac_f32_e32 v22, v26, v48
	v_fmac_f32_e32 v23, v27, v48
	v_cvt_pk_bf16_f32 v21, v22, v23
	global_store_dwordx2 v[150:151], v[20:21], off offset:64
	s_waitcnt vmcnt(3)
	v_lshlrev_b32_e32 v20, 16, v38
	v_fmac_f32_e32 v20, v16, v48
	v_and_b32_e32 v16, 0xffff0000, v38
	v_fmac_f32_e32 v16, v17, v48
	v_lshlrev_b32_e32 v17, 16, v39
	v_fmac_f32_e32 v17, v18, v48
	v_and_b32_e32 v18, 0xffff0000, v39
	v_fmac_f32_e32 v18, v19, v48
	v_cvt_pk_bf16_f32 v16, v20, v16
	v_cvt_pk_bf16_f32 v17, v17, v18
	global_store_dwordx2 v[150:151], v[16:17], off offset:96
	v_mov_b32_e32 v35, v63
	v_mov_b32_e32 v34, v63
	v_mov_b32_e32 v33, v63
	v_mov_b32_e32 v32, v63
	v_mov_b32_e32 v31, v63
	v_mov_b32_e32 v30, v63
	v_mov_b32_e32 v29, v63
	v_mov_b32_e32 v28, v63
	v_mov_b32_e32 v27, v63
	v_mov_b32_e32 v26, v63
	v_mov_b32_e32 v25, v63
	v_mov_b32_e32 v24, v63
	v_mov_b32_e32 v23, v63
	v_mov_b32_e32 v22, v63
	v_mov_b32_e32 v21, v63
	v_mov_b32_e32 v20, v63
	v_mov_b32_e32 v19, v63
	v_mov_b32_e32 v18, v63
	v_mov_b32_e32 v17, v63
	v_mov_b32_e32 v16, v63
	s_cbranch_scc1 .LBB0_873
	v_readlane_b32 s48, v250, 24
	v_readlane_b32 s49, v250, 25
	v_readlane_b32 s52, v250, 28
	v_readlane_b32 s53, v250, 29
	s_bitset1_b32 s38, 22
	s_mov_b64 s[48:49], s[52:53]
	s_add_u32 s2, s48, s43
	s_addc_u32 s3, s49, 0
	s_add_u32 s2, s2, s40
	s_addc_u32 s3, s3, s41
	v_lshl_add_u64 v[16:17], s[2:3], 0, v[84:85]
	v_lshl_add_u64 v[16:17], v[16:17], 0, v[116:117]
	s_mov_b64 s[2:3], 0x2000000
	v_lshl_add_u64 v[76:77], v[16:17], 0, s[2:3]
	s_lshl_b32 s2, s44, 6
	s_ashr_i32 s3, s2, 31
	v_lshl_add_u64 v[80:81], v[136:137], 0, s[38:39]
	s_lshl_b64 s[38:39], s[2:3], 7
	v_lshl_add_u64 v[16:17], v[76:77], 0, s[38:39]
	s_or_b32 s38, s2, 32
	s_ashr_i32 s39, s38, 31
	s_mov_b32 s46, 0x40000
	v_lshl_add_u64 v[28:29], s[2:3], 1, v[80:81]
	global_load_dwordx4 v[16:19], v[16:17], off
	s_nop 0
	global_load_dwordx4 v[20:23], v[28:29], off
	s_lshl_b64 s[38:39], s[38:39], 7
	v_lshl_add_u64 v[24:25], v[76:77], 0, s[38:39]
	v_add_co_u32_e32 v28, vcc, s46, v28
	global_load_dwordx4 v[24:27], v[24:25], off
	s_nop 0
	v_addc_co_u32_e32 v29, vcc, 0, v29, vcc
	global_load_dwordx4 v[28:31], v[28:29], off
	s_add_i32 s3, s44, 1
	s_cmp_lt_i32 s44, s33
	s_cselect_b32 s3, s3, s33
	s_lshl_b32 s38, s3, 6
	s_ashr_i32 s39, s38, 31
	s_lshl_b64 s[40:41], s[38:39], 7
	v_readlane_b32 s3, v248, 24
	v_mov_b32_e32 v153, 0
	v_mov_b32_e32 v156, 0
	v_mov_b32_e32 v32, 0
	v_mov_b32_e32 v33, v153
	v_mov_b32_e32 v34, v153
	v_mov_b32_e32 v35, v153
	v_mov_b32_e32 v52, 0
	v_mov_b32_e32 v53, v153
	v_mov_b32_e32 v54, v153
	v_mov_b32_e32 v55, v153
	v_mov_b32_e32 v56, 0
	v_mov_b32_e32 v57, v153
	v_mov_b32_e32 v58, v153
	v_mov_b32_e32 v59, v153
	v_mov_b32_e32 v60, 0
	v_mov_b32_e32 v61, v153
	v_mov_b32_e32 v62, v153
	v_mov_b32_e32 v63, v153
	v_readlane_b32 s50, v250, 26
	v_readlane_b32 s51, v250, 27
	v_readlane_b32 s54, v250, 30
	v_readlane_b32 s55, v250, 31
	v_readlane_b32 s56, v250, 32
	v_readlane_b32 s57, v250, 33
	v_readlane_b32 s58, v250, 34
	v_readlane_b32 s59, v250, 35
	v_readlane_b32 s60, v250, 36
	v_readlane_b32 s61, v250, 37
	v_readlane_b32 s62, v250, 38
	v_readlane_b32 s63, v250, 39
	s_waitcnt vmcnt(3)
	ds_write_b128 v127, v[16:19]
	s_waitcnt vmcnt(2)
	ds_write_b128 v127, v[20:23] offset:18432
	s_waitcnt vmcnt(1)
	ds_write_b128 v127, v[24:27] offset:4608
	s_waitcnt vmcnt(0)
	ds_write_b128 v127, v[28:31] offset:23040
	v_lshl_add_u64 v[16:17], s[38:39], 1, v[80:81]
	s_or_b32 s38, s38, 32
	v_lshl_add_u64 v[18:19], v[76:77], 0, s[40:41]
	s_ashr_i32 s39, s38, 31
	global_load_dwordx4 v[36:39], v[18:19], off
	global_load_dwordx4 v[40:43], v[16:17], off
	s_lshl_b64 s[38:39], s[38:39], 7
	v_add_co_u32_e32 v16, vcc, 0x40000, v16
	v_lshl_add_u64 v[18:19], v[76:77], 0, s[38:39]
	s_nop 0
	v_addc_co_u32_e32 v17, vcc, 0, v17, vcc
	global_load_dwordx4 v[44:47], v[18:19], off
	global_load_dwordx4 v[48:51], v[16:17], off
	v_add_u32_e32 v16, s3, v177
	v_readlane_b32 s3, v248, 27
	v_mov_b32_e32 v17, v153
	v_mov_b32_e32 v18, v153
	v_subrev_u32_e32 v16, s3, v16
	v_subrev_u32_e32 v113, s2, v16
	v_mov_b32_e32 v16, 0
	v_mov_b32_e32 v19, v153
	v_mov_b32_e32 v20, 0
	v_mov_b32_e32 v21, v153
	v_mov_b32_e32 v22, v153
	v_mov_b32_e32 v23, v153
	v_mov_b32_e32 v24, 0
	v_mov_b32_e32 v25, v153
	v_mov_b32_e32 v26, v153
	v_mov_b32_e32 v27, v153
	v_mov_b32_e32 v28, 0
	v_mov_b32_e32 v29, v153
	v_mov_b32_e32 v30, v153
	v_mov_b32_e32 v31, v153
	s_waitcnt lgkmcnt(0)
	s_barrier
	ds_read_b128 v[186:189], v129 offset:0
	ds_read_b128 v[190:193], v129 offset:64
	ds_read_b128 v[194:197], v129 offset:2304
	ds_read_b128 v[198:201], v129 offset:2368
	v_mov_b32_e32 v158, v153
	v_mov_b32_e32 v159, 0
	v_mov_b32_e32 v160, v156
	v_mov_b32_e32 v161, 0
.LBB0_872:
	s_add_i32 s2, s44, s42
	s_cmp_eq_u32 s42, 0
	s_cbranch_scc1 .Lwin_masked
	s_cmp_eq_u32 s2, s33
	s_cbranch_scc1 .Lwin_masked
	s_and_b32 s40, s42, 1
	s_xor_b32 s2, s40, 1
	s_mulk_i32 s2, 0x2400
	s_mulk_i32 s40, 0x2400
	v_add_u32_e32 v73, s40, v129
	v_add_u32_e32 v74, s2, v127
	v_add_u32_e32 v72, s40, v131
	ds_read_b128 v[202:205], v73 offset:4608
	ds_read_b128 v[206:209], v73 offset:4672
	ds_read_b128 v[210:213], v73 offset:6912
	ds_read_b128 v[218:221], v73 offset:6976
	v_add_u32_e32 v73, s2, v129
	s_waitcnt lgkmcnt(5)
	v_mfma_f32_16x16x32_bf16 v[64:67], v[186:189], v[0:3], 0
	v_mfma_f32_16x16x32_bf16 v[68:71], v[186:189], v[8:11], 0
	v_mfma_f32_16x16x32_bf16 v[222:225], v[194:197], v[0:3], 0
	v_mfma_f32_16x16x32_bf16 v[226:229], v[194:197], v[8:11], 0
	s_waitcnt vmcnt(2)
	ds_write_b128 v74, v[36:39]
	ds_write_b128 v74, v[40:43] offset:18432
	s_waitcnt lgkmcnt(6)
	v_mfma_f32_16x16x32_bf16 v[64:67], v[190:193], v[4:7], v[64:67]
	v_mfma_f32_16x16x32_bf16 v[68:71], v[190:193], v[12:15], v[68:71]
	v_mfma_f32_16x16x32_bf16 v[222:225], v[198:201], v[4:7], v[222:225]
	v_mfma_f32_16x16x32_bf16 v[226:229], v[198:201], v[12:15], v[226:229]
	s_waitcnt vmcnt(0)
	ds_write_b128 v74, v[44:47] offset:4608
	ds_write_b128 v74, v[48:51] offset:23040
	s_add_i32 s2, s44, s42
	s_add_i32 s2, s2, 2
	s_min_i32 s2, s2, s33
	s_lshl_b32 s2, s2, 6
	s_ashr_i32 s3, s2, 31
	s_lshl_b64 s[38:39], s[2:3], 7
	v_lshl_add_u64 v[40:41], s[2:3], 1, v[80:81]
	v_lshl_add_u64 v[36:37], v[76:77], 0, s[38:39]
	s_or_b32 s2, s2, 32
	s_ashr_i32 s3, s2, 31
	s_lshl_b64 s[2:3], s[2:3], 7
	global_load_dwordx4 v[36:39], v[36:37], off
	v_lshl_add_u64 v[44:45], v[76:77], 0, s[2:3]
	v_add_co_u32_e32 v48, vcc, s46, v40
	s_nop 0
	v_addc_co_u32_e32 v49, vcc, 0, v41, vcc
	global_load_dwordx4 v[40:43], v[40:41], off
	global_load_dwordx4 v[44:47], v[44:45], off
	global_load_dwordx4 v[48:51], v[48:49], off
	ds_read_b64 v[186:187], v72 offset:18432
	ds_read_b64 v[188:189], v72 offset:18464
	ds_read_b64 v[190:191], v72 offset:20736
	ds_read_b64 v[192:193], v72 offset:20768
	ds_read_b64 v[194:195], v72 offset:23040
	ds_read_b64 v[196:197], v72 offset:23072
	ds_read_b64 v[198:199], v72 offset:25344
	s_waitcnt lgkmcnt(13)
	ds_read_b64 v[200:201], v72 offset:25376
	s_waitcnt lgkmcnt(13)
	v_mfma_f32_16x16x32_bf16 v[230:233], v[202:205], v[0:3], 0
	v_mfma_f32_16x16x32_bf16 v[234:237], v[202:205], v[8:11], 0
	v_mfma_f32_16x16x32_bf16 v[238:241], v[210:213], v[0:3], 0
	v_mfma_f32_16x16x32_bf16 v[242:245], v[210:213], v[8:11], 0
	s_waitcnt lgkmcnt(12)
	v_mfma_f32_16x16x32_bf16 v[230:233], v[206:209], v[4:7], v[230:233]
	v_mfma_f32_16x16x32_bf16 v[234:237], v[206:209], v[12:15], v[234:237]
	v_mfma_f32_16x16x32_bf16 v[238:241], v[218:221], v[4:7], v[238:241]
	v_mfma_f32_16x16x32_bf16 v[242:245], v[218:221], v[12:15], v[242:245]
	ds_read_b64 v[202:203], v72 offset:18496
	ds_read_b64 v[204:205], v72 offset:18528
	ds_read_b64 v[206:207], v72 offset:20800
	s_waitcnt lgkmcnt(13)
	ds_read_b64 v[208:209], v72 offset:20832
	ds_read_b64 v[210:211], v72 offset:23104
	s_waitcnt lgkmcnt(13)
	ds_read_b64 v[212:213], v72 offset:23136
	ds_read_b64 v[218:219], v72 offset:25408
	s_waitcnt lgkmcnt(13)
	ds_read_b64 v[220:221], v72 offset:25440
	s_setprio 0
	s_add_i32 s2, s44, s42
	s_add_i32 s42, s42, 1
	v_subrev_u32_e32 v113, 64, v113
	v_exp_f32_e32 v64, v64
	v_exp_f32_e32 v68, v68
	v_exp_f32_e32 v65, v65
	v_exp_f32_e32 v69, v69
	v_exp_f32_e32 v66, v66
	v_exp_f32_e32 v70, v70
	v_exp_f32_e32 v67, v67
	v_exp_f32_e32 v71, v71
	v_pk_add_f32 v[158:159], v[158:159], v[64:65]
	v_pk_add_f32 v[160:161], v[160:161], v[68:69]
	v_pk_add_f32 v[158:159], v[158:159], v[66:67]
	v_pk_add_f32 v[160:161], v[160:161], v[70:71]
	v_exp_f32_e32 v222, v222
	v_exp_f32_e32 v226, v226
	v_exp_f32_e32 v223, v223
	v_exp_f32_e32 v227, v227
	v_exp_f32_e32 v224, v224
	v_exp_f32_e32 v228, v228
	v_exp_f32_e32 v225, v225
	v_exp_f32_e32 v229, v229
	v_pk_add_f32 v[158:159], v[158:159], v[222:223]
	v_pk_add_f32 v[160:161], v[160:161], v[226:227]
	v_pk_add_f32 v[158:159], v[158:159], v[224:225]
	v_pk_add_f32 v[160:161], v[160:161], v[228:229]
	s_waitcnt lgkmcnt(0)
	s_barrier
	v_cvt_pk_bf16_f32 v64, v64, v65
	v_cvt_pk_bf16_f32 v68, v68, v69
	v_cvt_pk_bf16_f32 v65, v66, v67
	v_cvt_pk_bf16_f32 v69, v70, v71
	v_cvt_pk_bf16_f32 v66, v222, v223
	v_cvt_pk_bf16_f32 v70, v226, v227
	v_cvt_pk_bf16_f32 v67, v224, v225
	v_cvt_pk_bf16_f32 v71, v228, v229
	v_exp_f32_e32 v230, v230
	v_exp_f32_e32 v234, v234
	v_mfma_f32_16x16x32_bf16 v[60:63], v[186:189], v[64:67], v[60:63]
	v_exp_f32_e32 v231, v231
	v_exp_f32_e32 v235, v235
	v_exp_f32_e32 v232, v232
	v_exp_f32_e32 v236, v236
	v_mfma_f32_16x16x32_bf16 v[28:31], v[186:189], v[68:71], v[28:31]
	v_exp_f32_e32 v233, v233
	v_exp_f32_e32 v237, v237
	v_pk_add_f32 v[158:159], v[158:159], v[230:231]
	v_pk_add_f32 v[160:161], v[160:161], v[234:235]
	v_mfma_f32_16x16x32_bf16 v[56:59], v[190:193], v[64:67], v[56:59]
	v_pk_add_f32 v[158:159], v[158:159], v[232:233]
	v_pk_add_f32 v[160:161], v[160:161], v[236:237]
	v_exp_f32_e32 v238, v238
	v_exp_f32_e32 v242, v242
	v_mfma_f32_16x16x32_bf16 v[24:27], v[190:193], v[68:71], v[24:27]
	v_exp_f32_e32 v239, v239
	v_exp_f32_e32 v243, v243
	v_exp_f32_e32 v240, v240
	v_exp_f32_e32 v244, v244
	v_mfma_f32_16x16x32_bf16 v[52:55], v[194:197], v[64:67], v[52:55]
	v_exp_f32_e32 v241, v241
	v_exp_f32_e32 v245, v245
	v_pk_add_f32 v[158:159], v[158:159], v[238:239]
	v_pk_add_f32 v[160:161], v[160:161], v[242:243]
	v_mfma_f32_16x16x32_bf16 v[20:23], v[194:197], v[68:71], v[20:23]
	v_pk_add_f32 v[158:159], v[158:159], v[240:241]
	v_pk_add_f32 v[160:161], v[160:161], v[244:245]
	v_cvt_pk_bf16_f32 v230, v230, v231
	v_cvt_pk_bf16_f32 v234, v234, v235
	v_mfma_f32_16x16x32_bf16 v[32:35], v[198:201], v[64:67], v[32:35]
	v_cvt_pk_bf16_f32 v231, v232, v233
	v_cvt_pk_bf16_f32 v235, v236, v237
	v_cvt_pk_bf16_f32 v232, v238, v239
	v_cvt_pk_bf16_f32 v236, v242, v243
	v_mfma_f32_16x16x32_bf16 v[16:19], v[198:201], v[68:71], v[16:19]
	v_cvt_pk_bf16_f32 v233, v240, v241
	v_cvt_pk_bf16_f32 v237, v244, v245
	ds_read_b128 v[186:189], v73 offset:0
	ds_read_b128 v[190:193], v73 offset:64
	ds_read_b128 v[194:197], v73 offset:2304
	ds_read_b128 v[198:201], v73 offset:2368
	s_setprio 2
	v_mfma_f32_16x16x32_bf16 v[60:63], v[202:205], v[230:233], v[60:63]
	v_mfma_f32_16x16x32_bf16 v[28:31], v[202:205], v[234:237], v[28:31]
	v_mfma_f32_16x16x32_bf16 v[56:59], v[206:209], v[230:233], v[56:59]
	v_mfma_f32_16x16x32_bf16 v[24:27], v[206:209], v[234:237], v[24:27]
	v_mfma_f32_16x16x32_bf16 v[52:55], v[210:213], v[230:233], v[52:55]
	v_mfma_f32_16x16x32_bf16 v[20:23], v[210:213], v[234:237], v[20:23]
	v_mfma_f32_16x16x32_bf16 v[32:35], v[218:221], v[230:233], v[32:35]
	v_mfma_f32_16x16x32_bf16 v[16:19], v[218:221], v[234:237], v[16:19]
	s_cmp_lt_i32 s2, s33
	s_cbranch_scc1 .LBB0_872
	s_branch .Lwin_done
.Lwin_masked:
	s_and_b32 s40, s42, 1
	s_xor_b32 s2, s40, 1
	s_mulk_i32 s2, 0x2400
	s_mulk_i32 s40, 0x2400
	v_add_u32_e32 v73, s40, v129
	v_add_u32_e32 v74, s2, v127
	v_add_u32_e32 v72, s40, v131
	ds_read_b128 v[202:205], v73 offset:4608
	ds_read_b128 v[206:209], v73 offset:4672
	ds_read_b128 v[210:213], v73 offset:6912
	ds_read_b128 v[218:221], v73 offset:6976
	v_add_u32_e32 v73, s2, v129
	v_add_u32_e32 v75, -4, v113
	v_min_i32_e32 v157, 63, v75
	v_sub_u32_e32 v157, 63, v157
	v_mov_b32_e32 v246, -1
	v_mov_b32_e32 v247, -1
	v_lshrrev_b64 v[246:247], v157, v[246:247]
	v_add_u32_e32 v162, 0xfffffe01, v75
	v_med3_i32 v162, v162, 0, 64
	v_min_u32_e32 v163, 32, v162
	v_sub_u32_e32 v162, v162, v163
	v_mov_b32_e32 v238, -1
	v_mov_b32_e32 v239, -1
	v_lshlrev_b64 v[238:239], v163, v[238:239]
	v_lshlrev_b64 v[238:239], v162, v[238:239]
	v_and_b32_e32 v246, v246, v238
	v_and_b32_e32 v247, v247, v239
	v_lshrrev_b32_e32 v246, v112, v246
	v_lshrrev_b32_e32 v247, v112, v247
	v_mov_b32_e32 v75, v113
	v_min_i32_e32 v157, 63, v75
	v_sub_u32_e32 v157, 63, v157
	v_mov_b32_e32 v184, -1
	v_mov_b32_e32 v185, -1
	v_lshrrev_b64 v[184:185], v157, v[184:185]
	v_add_u32_e32 v162, 0xfffffe01, v75
	v_med3_i32 v162, v162, 0, 64
	v_min_u32_e32 v163, 32, v162
	v_sub_u32_e32 v162, v162, v163
	v_mov_b32_e32 v242, -1
	v_mov_b32_e32 v243, -1
	v_lshlrev_b64 v[242:243], v163, v[242:243]
	v_lshlrev_b64 v[242:243], v162, v[242:243]
	v_and_b32_e32 v184, v184, v242
	v_and_b32_e32 v185, v185, v243
	v_lshrrev_b32_e32 v184, v112, v184
	v_lshrrev_b32_e32 v185, v112, v185
	s_waitcnt lgkmcnt(5)
	v_mfma_f32_16x16x32_bf16 v[64:67], v[186:189], v[0:3], 0
	v_mfma_f32_16x16x32_bf16 v[68:71], v[186:189], v[8:11], 0
	v_mfma_f32_16x16x32_bf16 v[222:225], v[194:197], v[0:3], 0
	v_mfma_f32_16x16x32_bf16 v[226:229], v[194:197], v[8:11], 0
	s_waitcnt vmcnt(2)
	ds_write_b128 v74, v[36:39]
	ds_write_b128 v74, v[40:43] offset:18432
	s_waitcnt lgkmcnt(6)
	v_mfma_f32_16x16x32_bf16 v[64:67], v[190:193], v[4:7], v[64:67]
	v_mfma_f32_16x16x32_bf16 v[68:71], v[190:193], v[12:15], v[68:71]
	v_mfma_f32_16x16x32_bf16 v[222:225], v[198:201], v[4:7], v[222:225]
	v_mfma_f32_16x16x32_bf16 v[226:229], v[198:201], v[12:15], v[226:229]
	s_waitcnt vmcnt(0)
	ds_write_b128 v74, v[44:47] offset:4608
	ds_write_b128 v74, v[48:51] offset:23040
	s_add_i32 s2, s44, s42
	s_add_i32 s2, s2, 2
	s_min_i32 s2, s2, s33
	s_lshl_b32 s2, s2, 6
	s_ashr_i32 s3, s2, 31
	s_lshl_b64 s[38:39], s[2:3], 7
	v_lshl_add_u64 v[40:41], s[2:3], 1, v[80:81]
	v_lshl_add_u64 v[36:37], v[76:77], 0, s[38:39]
	s_or_b32 s2, s2, 32
	s_ashr_i32 s3, s2, 31
	s_lshl_b64 s[2:3], s[2:3], 7
	global_load_dwordx4 v[36:39], v[36:37], off
	v_lshl_add_u64 v[44:45], v[76:77], 0, s[2:3]
	v_add_co_u32_e32 v48, vcc, s46, v40
	s_nop 0
	v_addc_co_u32_e32 v49, vcc, 0, v41, vcc
	global_load_dwordx4 v[40:43], v[40:41], off
	global_load_dwordx4 v[44:47], v[44:45], off
	global_load_dwordx4 v[48:51], v[48:49], off
	ds_read_b64 v[186:187], v72 offset:18432
	ds_read_b64 v[188:189], v72 offset:18464
	ds_read_b64 v[190:191], v72 offset:20736
	ds_read_b64 v[192:193], v72 offset:20768
	ds_read_b64 v[194:195], v72 offset:23040
	ds_read_b64 v[196:197], v72 offset:23072
	ds_read_b64 v[198:199], v72 offset:25344
	s_waitcnt lgkmcnt(13)
	ds_read_b64 v[200:201], v72 offset:25376
	s_waitcnt lgkmcnt(13)
	v_mfma_f32_16x16x32_bf16 v[230:233], v[202:205], v[0:3], 0
	v_mfma_f32_16x16x32_bf16 v[234:237], v[202:205], v[8:11], 0
	v_mfma_f32_16x16x32_bf16 v[238:241], v[210:213], v[0:3], 0
	v_mfma_f32_16x16x32_bf16 v[242:245], v[210:213], v[8:11], 0
	s_waitcnt lgkmcnt(12)
	v_mfma_f32_16x16x32_bf16 v[230:233], v[206:209], v[4:7], v[230:233]
	v_mfma_f32_16x16x32_bf16 v[234:237], v[206:209], v[12:15], v[234:237]
	v_mfma_f32_16x16x32_bf16 v[238:241], v[218:221], v[4:7], v[238:241]
	v_mfma_f32_16x16x32_bf16 v[242:245], v[218:221], v[12:15], v[242:245]
	ds_read_b64 v[202:203], v72 offset:18496
	ds_read_b64 v[204:205], v72 offset:18528
	ds_read_b64 v[206:207], v72 offset:20800
	s_waitcnt lgkmcnt(13)
	ds_read_b64 v[208:209], v72 offset:20832
	ds_read_b64 v[210:211], v72 offset:23104
	s_waitcnt lgkmcnt(13)
	ds_read_b64 v[212:213], v72 offset:23136
	ds_read_b64 v[218:219], v72 offset:25408
	s_waitcnt lgkmcnt(13)
	ds_read_b64 v[220:221], v72 offset:25440
	s_setprio 0
	s_add_i32 s2, s44, s42
	s_add_i32 s42, s42, 1
	v_subrev_u32_e32 v113, 64, v113
	v_exp_f32_e32 v64, v64
	v_exp_f32_e32 v68, v68
	v_exp_f32_e32 v65, v65
	v_exp_f32_e32 v69, v69
	v_exp_f32_e32 v66, v66
	v_exp_f32_e32 v70, v70
	v_exp_f32_e32 v67, v67
	v_exp_f32_e32 v71, v71
	v_bfe_i32 v75, v246, 0, 1
	v_bfe_i32 v162, v184, 0, 1
	v_bfe_i32 v157, v246, 1, 1
	v_bfe_i32 v163, v184, 1, 1
	v_and_b32_e32 v64, v75, v64
	v_and_b32_e32 v68, v162, v68
	v_and_b32_e32 v65, v157, v65
	v_and_b32_e32 v69, v163, v69
	v_bfe_i32 v75, v246, 2, 1
	v_bfe_i32 v162, v184, 2, 1
	v_bfe_i32 v157, v246, 3, 1
	v_bfe_i32 v163, v184, 3, 1
	v_and_b32_e32 v66, v75, v66
	v_and_b32_e32 v70, v162, v70
	v_and_b32_e32 v67, v157, v67
	v_and_b32_e32 v71, v163, v71
	v_pk_add_f32 v[158:159], v[158:159], v[64:65]
	v_pk_add_f32 v[160:161], v[160:161], v[68:69]
	v_pk_add_f32 v[158:159], v[158:159], v[66:67]
	v_pk_add_f32 v[160:161], v[160:161], v[70:71]
	v_exp_f32_e32 v222, v222
	v_exp_f32_e32 v226, v226
	v_exp_f32_e32 v223, v223
	v_exp_f32_e32 v227, v227
	v_exp_f32_e32 v224, v224
	v_exp_f32_e32 v228, v228
	v_exp_f32_e32 v225, v225
	v_exp_f32_e32 v229, v229
	v_bfe_i32 v75, v246, 16, 1
	v_bfe_i32 v162, v184, 16, 1
	v_bfe_i32 v157, v246, 17, 1
	v_bfe_i32 v163, v184, 17, 1
	v_and_b32_e32 v222, v75, v222
	v_and_b32_e32 v226, v162, v226
	v_and_b32_e32 v223, v157, v223
	v_and_b32_e32 v227, v163, v227
	v_bfe_i32 v75, v246, 18, 1
	v_bfe_i32 v162, v184, 18, 1
	v_bfe_i32 v157, v246, 19, 1
	v_bfe_i32 v163, v184, 19, 1
	v_and_b32_e32 v224, v75, v224
	v_and_b32_e32 v228, v162, v228
	v_and_b32_e32 v225, v157, v225
	v_and_b32_e32 v229, v163, v229
	v_pk_add_f32 v[158:159], v[158:159], v[222:223]
	v_pk_add_f32 v[160:161], v[160:161], v[226:227]
	v_pk_add_f32 v[158:159], v[158:159], v[224:225]
	v_pk_add_f32 v[160:161], v[160:161], v[228:229]
	s_waitcnt lgkmcnt(0)
	s_barrier
	v_cvt_pk_bf16_f32 v64, v64, v65
	v_cvt_pk_bf16_f32 v68, v68, v69
	v_cvt_pk_bf16_f32 v65, v66, v67
	v_cvt_pk_bf16_f32 v69, v70, v71
	v_cvt_pk_bf16_f32 v66, v222, v223
	v_cvt_pk_bf16_f32 v70, v226, v227
	v_cvt_pk_bf16_f32 v67, v224, v225
	v_cvt_pk_bf16_f32 v71, v228, v229
	v_exp_f32_e32 v230, v230
	v_exp_f32_e32 v234, v234
	v_mfma_f32_16x16x32_bf16 v[60:63], v[186:189], v[64:67], v[60:63]
	v_exp_f32_e32 v231, v231
	v_exp_f32_e32 v235, v235
	v_exp_f32_e32 v232, v232
	v_exp_f32_e32 v236, v236
	v_exp_f32_e32 v233, v233
	v_exp_f32_e32 v237, v237
	v_bfe_i32 v75, v247, 0, 1
	v_bfe_i32 v162, v185, 0, 1
	v_mfma_f32_16x16x32_bf16 v[28:31], v[186:189], v[68:71], v[28:31]
	v_bfe_i32 v157, v247, 1, 1
	v_bfe_i32 v163, v185, 1, 1
	v_and_b32_e32 v230, v75, v230
	v_and_b32_e32 v234, v162, v234
	v_and_b32_e32 v231, v157, v231
	v_and_b32_e32 v235, v163, v235
	v_bfe_i32 v75, v247, 2, 1
	v_bfe_i32 v162, v185, 2, 1
	v_mfma_f32_16x16x32_bf16 v[56:59], v[190:193], v[64:67], v[56:59]
	v_bfe_i32 v157, v247, 3, 1
	v_bfe_i32 v163, v185, 3, 1
	v_and_b32_e32 v232, v75, v232
	v_and_b32_e32 v236, v162, v236
	v_and_b32_e32 v233, v157, v233
	v_and_b32_e32 v237, v163, v237
	v_pk_add_f32 v[158:159], v[158:159], v[230:231]
	v_pk_add_f32 v[160:161], v[160:161], v[234:235]
	v_mfma_f32_16x16x32_bf16 v[24:27], v[190:193], v[68:71], v[24:27]
	v_pk_add_f32 v[158:159], v[158:159], v[232:233]
	v_pk_add_f32 v[160:161], v[160:161], v[236:237]
	v_exp_f32_e32 v238, v238
	v_exp_f32_e32 v242, v242
	v_exp_f32_e32 v239, v239
	v_exp_f32_e32 v243, v243
	v_exp_f32_e32 v240, v240
	v_exp_f32_e32 v244, v244
	v_mfma_f32_16x16x32_bf16 v[52:55], v[194:197], v[64:67], v[52:55]
	v_exp_f32_e32 v241, v241
	v_exp_f32_e32 v245, v245
	v_bfe_i32 v75, v247, 16, 1
	v_bfe_i32 v162, v185, 16, 1
	v_bfe_i32 v157, v247, 17, 1
	v_bfe_i32 v163, v185, 17, 1
	v_and_b32_e32 v238, v75, v238
	v_and_b32_e32 v242, v162, v242
	v_mfma_f32_16x16x32_bf16 v[20:23], v[194:197], v[68:71], v[20:23]
	v_and_b32_e32 v239, v157, v239
	v_and_b32_e32 v243, v163, v243
	v_bfe_i32 v75, v247, 18, 1
	v_bfe_i32 v162, v185, 18, 1
	v_bfe_i32 v157, v247, 19, 1
	v_bfe_i32 v163, v185, 19, 1
	v_and_b32_e32 v240, v75, v240
	v_and_b32_e32 v244, v162, v244
	v_mfma_f32_16x16x32_bf16 v[32:35], v[198:201], v[64:67], v[32:35]
	v_and_b32_e32 v241, v157, v241
	v_and_b32_e32 v245, v163, v245
	v_pk_add_f32 v[158:159], v[158:159], v[238:239]
	v_pk_add_f32 v[160:161], v[160:161], v[242:243]
	v_pk_add_f32 v[158:159], v[158:159], v[240:241]
	v_pk_add_f32 v[160:161], v[160:161], v[244:245]
	v_cvt_pk_bf16_f32 v230, v230, v231
	v_cvt_pk_bf16_f32 v234, v234, v235
	v_mfma_f32_16x16x32_bf16 v[16:19], v[198:201], v[68:71], v[16:19]
	v_cvt_pk_bf16_f32 v231, v232, v233
	v_cvt_pk_bf16_f32 v235, v236, v237
	v_cvt_pk_bf16_f32 v232, v238, v239
	v_cvt_pk_bf16_f32 v236, v242, v243
	v_cvt_pk_bf16_f32 v233, v240, v241
	v_cvt_pk_bf16_f32 v237, v244, v245
	ds_read_b128 v[186:189], v73 offset:0
	ds_read_b128 v[190:193], v73 offset:64
	ds_read_b128 v[194:197], v73 offset:2304
	ds_read_b128 v[198:201], v73 offset:2368
	s_setprio 2
	v_mfma_f32_16x16x32_bf16 v[60:63], v[202:205], v[230:233], v[60:63]
	v_mfma_f32_16x16x32_bf16 v[28:31], v[202:205], v[234:237], v[28:31]
	v_mfma_f32_16x16x32_bf16 v[56:59], v[206:209], v[230:233], v[56:59]
	v_mfma_f32_16x16x32_bf16 v[24:27], v[206:209], v[234:237], v[24:27]
	v_mfma_f32_16x16x32_bf16 v[52:55], v[210:213], v[230:233], v[52:55]
	v_mfma_f32_16x16x32_bf16 v[20:23], v[210:213], v[234:237], v[20:23]
	v_mfma_f32_16x16x32_bf16 v[32:35], v[218:221], v[230:233], v[32:35]
	v_mfma_f32_16x16x32_bf16 v[16:19], v[218:221], v[234:237], v[16:19]
	s_cmp_lt_i32 s2, s33
	s_cbranch_scc1 .LBB0_872
.Lwin_done:
	s_waitcnt lgkmcnt(0)
	s_setprio 0
	v_add_f32_e32 v153, v158, v159
	v_add_f32_e32 v156, v160, v161
